# hipcc's 11-instruction f32 division chains for silu/sigmoid (denominator 1+exp >= 1) in the mLSTM phases replaced by rcp, mul, fma remainder, fma correction, div_fixup (5 VALU, same specials handling,
# speedup vs baseline: 1.0192x; 1.0035x over previous
.LBB0_475:
	v_lshlrev_b32_e32 v54, 2, v52
	v_mov_b32_e32 v55, v179
	v_lshl_add_u64 v[66:67], s[28:29], 0, v[54:55]
	s_mov_b64 s[0:1], 0x1800
	s_waitcnt lgkmcnt(0)
	s_barrier
	global_load_dwordx4 v[50:53], v54, s[28:29] offset:2064
	global_load_dwordx4 v[70:73], v54, s[28:29] offset:2048
	v_lshl_add_u64 v[54:55], v[66:67], 0, s[0:1]
	v_add_co_u32_e32 v56, vcc, 0x1000, v66
	s_mov_b64 s[0:1], 0x2800
	s_nop 0
	v_addc_co_u32_e32 v57, vcc, 0, v67, vcc
	v_lshl_add_u64 v[58:59], v[66:67], 0, s[0:1]
	s_movk_i32 s0, 0x2000
	v_add_co_u32_e32 v60, vcc, s0, v66
	s_mov_b64 s[0:1], 0x3800
	s_nop 0
	v_addc_co_u32_e32 v61, vcc, 0, v67, vcc
	v_lshl_add_u64 v[62:63], v[66:67], 0, s[0:1]
	v_add_co_u32_e32 v64, vcc, 0x3000, v66
	s_mov_b64 s[0:1], 0x4800
	global_load_dwordx4 v[74:77], v[56:57], off offset:2048
	s_nop 0
	global_load_dwordx4 v[54:57], v[54:55], off offset:16
	v_addc_co_u32_e32 v65, vcc, 0, v67, vcc
	v_lshl_add_u64 v[68:69], v[66:67], 0, s[0:1]
	s_movk_i32 s0, 0x4000
	global_load_dwordx4 v[78:81], v[60:61], off offset:2048
	s_nop 0
	global_load_dwordx4 v[58:61], v[58:59], off offset:16
	v_add_co_u32_e32 v66, vcc, s0, v66
	global_load_dwordx4 v[82:85], v[64:65], off offset:2048
	s_nop 0
	global_load_dwordx4 v[62:65], v[62:63], off offset:16
	v_addc_co_u32_e32 v67, vcc, 0, v67, vcc
	global_load_dwordx4 v[86:89], v[66:67], off offset:2048
	s_nop 0
	global_load_dwordx4 v[66:69], v[68:69], off offset:16
	s_waitcnt vmcnt(14)
	v_lshlrev_b32_e32 v112, 16, v22
	v_and_b32_e32 v113, 0xffff0000, v22
	v_lshlrev_b32_e32 v108, 16, v26
	v_and_b32_e32 v109, 0xffff0000, v26
	v_lshlrev_b32_e32 v106, 16, v30
	v_and_b32_e32 v107, 0xffff0000, v30
	v_lshlrev_b32_e32 v90, 16, v34
	v_and_b32_e32 v91, 0xffff0000, v34
	v_lshlrev_b32_e32 v92, 16, v42
	v_and_b32_e32 v93, 0xffff0000, v42
	v_lshlrev_b32_e32 v94, 16, v38
	v_and_b32_e32 v95, 0xffff0000, v38
	v_lshlrev_b32_e32 v96, 16, v46
	v_and_b32_e32 v97, 0xffff0000, v46
	v_lshlrev_b32_e32 v42, 16, v43
	v_and_b32_e32 v43, 0xffff0000, v43
	v_lshlrev_b32_e32 v46, 16, v47
	v_and_b32_e32 v47, 0xffff0000, v47
	s_add_i32 s8, 0, 0x18a00
	s_ashr_i32 s5, s60, 8
	s_and_b32 s4, s82, 3
	s_waitcnt vmcnt(8)
	v_pk_fma_f32 v[112:113], v[70:71], v[112:113], 0 op_sel_hi:[1,1,0]
	v_pk_fma_f32 v[110:111], v[70:71], v[108:109], 0 op_sel_hi:[1,1,0]
	v_pk_fma_f32 v[98:99], v[70:71], v[106:107], 0 op_sel_hi:[1,1,0]
	v_pk_fma_f32 v[70:71], v[70:71], v[90:91], 0 op_sel_hi:[1,1,0]
	s_waitcnt vmcnt(7)
	v_pk_fma_f32 v[108:109], v[74:75], v[108:109], v[112:113]
	v_pk_fma_f32 v[110:111], v[74:75], v[106:107], v[110:111]
	v_pk_fma_f32 v[98:99], v[74:75], v[90:91], v[98:99]
	v_pk_fma_f32 v[70:71], v[74:75], v[92:93], v[70:71]
	v_lshlrev_b32_e32 v74, 16, v18
	s_waitcnt vmcnt(5)
	v_pk_fma_f32 v[106:107], v[78:79], v[106:107], v[108:109]
	v_pk_fma_f32 v[98:99], v[78:79], v[92:93], v[98:99]
	v_pk_fma_f32 v[70:71], v[78:79], v[94:95], v[70:71]
	s_waitcnt vmcnt(3)
	v_pk_fma_f32 v[106:107], v[82:83], v[90:91], v[106:107]
	v_pk_fma_f32 v[98:99], v[82:83], v[94:95], v[98:99]
	v_pk_fma_f32 v[70:71], v[82:83], v[96:97], v[70:71]
	s_waitcnt vmcnt(1)
	v_pk_fma_f32 v[106:107], v[86:87], v[92:93], v[106:107]
	v_pk_fma_f32 v[98:99], v[86:87], v[96:97], v[98:99]
	v_mul_f32_e32 v22, 0xbfb8aa3b, v106
	v_exp_f32_e32 v108, v22
	v_mul_f32_e32 v22, 0xbfb8aa3b, v107
	v_exp_f32_e32 v109, v22
	v_and_b32_e32 v75, 0xffff0000, v18
	v_pk_fma_f32 v[70:71], v[86:87], v[74:75], v[70:71]
	v_pk_add_f32 v[108:109], v[108:109], 1.0 op_sel_hi:[1,0]
	s_nop 0
	v_rcp_f32_e32 v26, v109
	v_mul_f32_e32 v18, 0xbfb8aa3b, v70
	v_exp_f32_e32 v74, v18
	v_mul_f32_e32 v18, 0xbfb8aa3b, v71
	s_nop 0
	v_mul_f32_e32 v34, v107, v26
	v_fma_f32 v38, -v109, v34, v107
	v_fma_f32 v22, v38, v26, v34
	v_div_fixup_f32 v107, v22, v109, v107
	v_rcp_f32_e32 v26, v108
	v_exp_f32_e32 v75, v18
	s_nop 0
	v_mul_f32_e32 v34, v106, v26
	v_fma_f32 v38, -v108, v34, v106
	v_fma_f32 v22, v38, v26, v34
	v_div_fixup_f32 v106, v22, v108, v106
	v_pk_mul_f32 v[106:107], v[106:107], s[26:27] op_sel_hi:[1,0]
	v_pk_add_f32 v[74:75], v[74:75], 1.0 op_sel_hi:[1,0]
	v_cvt_pk_bf16_f32 v105, v106, v107
	v_pk_fma_f32 v[106:107], v[78:79], v[90:91], v[110:111]
	v_pk_fma_f32 v[106:107], v[82:83], v[92:93], v[106:107]
	s_nop 0
	v_pk_fma_f32 v[106:107], v[86:87], v[94:95], v[106:107]
	s_nop 0
	v_mul_f32_e32 v22, 0xbfb8aa3b, v106
	v_exp_f32_e32 v108, v22
	v_mul_f32_e32 v22, 0xbfb8aa3b, v107
	v_exp_f32_e32 v109, v22
	s_nop 0
	v_pk_add_f32 v[108:109], v[108:109], 1.0 op_sel_hi:[1,0]
	s_nop 0
	v_rcp_f32_e32 v26, v109
	s_nop 0
	s_nop 0
	v_mul_f32_e32 v34, v107, v26
	v_fma_f32 v38, -v109, v34, v107
	v_fma_f32 v22, v38, v26, v34
	v_div_fixup_f32 v107, v22, v109, v107
	v_rcp_f32_e32 v26, v108
	s_nop 0
	s_nop 0
	v_mul_f32_e32 v34, v106, v26
	v_fma_f32 v38, -v108, v34, v106
	v_fma_f32 v22, v38, v26, v34
	v_div_fixup_f32 v106, v22, v108, v106
	v_mul_f32_e32 v22, 0xbfb8aa3b, v98
	v_exp_f32_e32 v108, v22
	v_mul_f32_e32 v22, 0xbfb8aa3b, v99
	v_exp_f32_e32 v109, v22
	v_pk_mul_f32 v[106:107], v[106:107], s[26:27] op_sel_hi:[1,0]
	v_pk_add_f32 v[108:109], v[108:109], 1.0 op_sel_hi:[1,0]
	s_nop 0
	v_rcp_f32_e32 v26, v109
	v_cvt_pk_bf16_f32 v106, v106, v107
	s_nop 0
	v_mul_f32_e32 v34, v99, v26
	v_fma_f32 v38, -v109, v34, v99
	v_fma_f32 v22, v38, v26, v34
	v_div_fixup_f32 v99, v22, v109, v99
	v_rcp_f32_e32 v26, v108
	s_nop 0
	s_nop 0
	v_mul_f32_e32 v34, v98, v26
	v_fma_f32 v38, -v108, v34, v98
	v_fma_f32 v22, v38, v26, v34
	v_div_fixup_f32 v98, v22, v108, v98
	v_rcp_f32_e32 v22, v75
	v_lshlrev_b32_e32 v38, 16, v39
	v_and_b32_e32 v39, 0xffff0000, v39
	v_pk_mul_f32 v[98:99], v[98:99], s[26:27] op_sel_hi:[1,0]
	s_nop 0
	v_mul_f32_e32 v30, v71, v22
	v_fma_f32 v34, -v75, v30, v71
	v_fma_f32 v18, v34, v22, v30
	v_div_fixup_f32 v71, v18, v75, v71
	v_rcp_f32_e32 v22, v74
	v_and_b32_e32 v75, 0xffff0000, v31
	v_cvt_pk_bf16_f32 v98, v98, v99
	s_nop 0
	v_mul_f32_e32 v30, v70, v22
	v_fma_f32 v34, -v74, v30, v70
	v_fma_f32 v18, v34, v22, v30
	v_lshlrev_b32_e32 v22, 16, v23
	v_and_b32_e32 v23, 0xffff0000, v23
	v_lshlrev_b32_e32 v26, 16, v27
	v_and_b32_e32 v27, 0xffff0000, v27
	v_pk_fma_f32 v[22:23], v[72:73], v[22:23], 0 op_sel_hi:[1,1,0]
	v_div_fixup_f32 v70, v18, v74, v70
	v_lshlrev_b32_e32 v74, 16, v31
	v_pk_fma_f32 v[22:23], v[76:77], v[26:27], v[22:23]
	v_lshlrev_b32_e32 v34, 16, v35
	v_and_b32_e32 v35, 0xffff0000, v35
	v_pk_fma_f32 v[22:23], v[80:81], v[74:75], v[22:23]
	v_pk_fma_f32 v[78:79], v[72:73], v[26:27], 0 op_sel_hi:[1,1,0]
	v_pk_fma_f32 v[22:23], v[84:85], v[34:35], v[22:23]
	v_pk_fma_f32 v[30:31], v[72:73], v[74:75], 0 op_sel_hi:[1,1,0]
	v_pk_fma_f32 v[22:23], v[88:89], v[42:43], v[22:23]
	v_pk_fma_f32 v[78:79], v[76:77], v[74:75], v[78:79]
	v_mul_f32_e32 v18, 0xbfb8aa3b, v22
	v_exp_f32_e32 v26, v18
	v_mul_f32_e32 v18, 0xbfb8aa3b, v23
	v_exp_f32_e32 v27, v18
	v_pk_mul_f32 v[70:71], v[70:71], s[26:27] op_sel_hi:[1,0]
	v_pk_add_f32 v[26:27], v[26:27], 1.0 op_sel_hi:[1,0]
	s_nop 0
	v_rcp_f32_e32 v74, v27
	s_nop 0
	s_nop 0
	v_mul_f32_e32 v82, v23, v74
	v_fma_f32 v83, -v27, v82, v23
	v_fma_f32 v18, v83, v74, v82
	v_div_fixup_f32 v23, v18, v27, v23
	v_rcp_f32_e32 v27, v26
	s_nop 0
	s_nop 0
	v_mul_f32_e32 v75, v22, v27
	v_fma_f32 v82, -v26, v75, v22
	v_fma_f32 v18, v82, v27, v75
	v_div_fixup_f32 v22, v18, v26, v22
	v_pk_mul_f32 v[22:23], v[22:23], s[26:27] op_sel_hi:[1,0]
	s_nop 0
	v_cvt_pk_bf16_f32 v74, v22, v23
	v_pk_fma_f32 v[22:23], v[80:81], v[34:35], v[78:79]
	s_nop 0
	v_pk_fma_f32 v[22:23], v[84:85], v[42:43], v[22:23]
	s_nop 0
	v_pk_fma_f32 v[22:23], v[88:89], v[38:39], v[22:23]
	s_nop 0
	v_mul_f32_e32 v18, 0xbfb8aa3b, v22
	v_exp_f32_e32 v26, v18
	v_mul_f32_e32 v18, 0xbfb8aa3b, v23
	v_exp_f32_e32 v27, v18
	s_nop 0
	v_pk_add_f32 v[26:27], v[26:27], 1.0 op_sel_hi:[1,0]
	s_nop 0
	v_rcp_f32_e32 v75, v27
	s_nop 0
	s_nop 0
	v_mul_f32_e32 v79, v23, v75
	v_fma_f32 v82, -v27, v79, v23
	v_fma_f32 v18, v82, v75, v79
	v_div_fixup_f32 v23, v18, v27, v23
	v_rcp_f32_e32 v27, v26
	s_nop 0
	s_nop 0
	v_mul_f32_e32 v78, v22, v27
	v_fma_f32 v79, -v26, v78, v22
	v_fma_f32 v18, v79, v27, v78
	v_div_fixup_f32 v22, v18, v26, v22
	v_pk_mul_f32 v[22:23], v[22:23], s[26:27] op_sel_hi:[1,0]
	s_nop 0
	v_cvt_pk_bf16_f32 v75, v22, v23
	v_pk_fma_f32 v[22:23], v[76:77], v[34:35], v[30:31]
	s_nop 0
	v_pk_fma_f32 v[22:23], v[80:81], v[42:43], v[22:23]
	s_nop 0
	v_pk_fma_f32 v[22:23], v[84:85], v[38:39], v[22:23]
	s_nop 0
	v_pk_fma_f32 v[22:23], v[88:89], v[46:47], v[22:23]
	s_nop 0
	v_mul_f32_e32 v18, 0xbfb8aa3b, v22
	v_exp_f32_e32 v26, v18
	v_mul_f32_e32 v18, 0xbfb8aa3b, v23
	v_exp_f32_e32 v27, v18
	s_nop 0
	v_pk_add_f32 v[26:27], v[26:27], 1.0 op_sel_hi:[1,0]
	s_nop 0
	v_rcp_f32_e32 v30, v27
	s_nop 0
	s_nop 0
	v_mul_f32_e32 v78, v23, v30
	v_fma_f32 v79, -v27, v78, v23
	v_fma_f32 v18, v79, v30, v78
	v_div_fixup_f32 v23, v18, v27, v23
	v_rcp_f32_e32 v27, v26
	s_nop 0
	s_nop 0
	v_mul_f32_e32 v31, v22, v27
	v_fma_f32 v78, -v26, v31, v22
	v_fma_f32 v18, v78, v27, v31
	v_div_fixup_f32 v22, v18, v26, v22
	v_pk_mul_f32 v[22:23], v[22:23], s[26:27] op_sel_hi:[1,0]
	v_lshlrev_b32_e32 v18, 16, v19
	v_cvt_pk_bf16_f32 v78, v22, v23
	v_pk_fma_f32 v[22:23], v[72:73], v[34:35], 0 op_sel_hi:[1,1,0]
	v_and_b32_e32 v19, 0xffff0000, v19
	v_pk_fma_f32 v[22:23], v[76:77], v[42:43], v[22:23]
	v_lshlrev_b32_e32 v76, 16, v24
	v_pk_fma_f32 v[22:23], v[80:81], v[38:39], v[22:23]
	v_and_b32_e32 v77, 0xffff0000, v24
	v_pk_fma_f32 v[22:23], v[84:85], v[46:47], v[22:23]
	v_lshlrev_b32_e32 v46, 16, v28
	v_pk_fma_f32 v[18:19], v[88:89], v[18:19], v[22:23]
	v_and_b32_e32 v47, 0xffff0000, v28
	v_mul_f32_e32 v22, 0xbfb8aa3b, v18
	v_mul_f32_e32 v23, 0xbfb8aa3b, v19
	v_exp_f32_e32 v22, v22
	v_exp_f32_e32 v23, v23
	v_pk_fma_f32 v[76:77], v[50:51], v[76:77], 0 op_sel_hi:[1,1,0]
	v_lshlrev_b32_e32 v42, 16, v32
	v_and_b32_e32 v43, 0xffff0000, v32
	v_pk_add_f32 v[22:23], v[22:23], 1.0 op_sel_hi:[1,0]
	v_pk_fma_f32 v[72:73], v[50:51], v[46:47], 0 op_sel_hi:[1,1,0]
	v_rcp_f32_e32 v27, v23
	v_pk_fma_f32 v[46:47], v[54:55], v[46:47], v[76:77]
	v_pk_fma_f32 v[38:39], v[50:51], v[42:43], 0 op_sel_hi:[1,1,0]
	v_pk_fma_f32 v[72:73], v[54:55], v[42:43], v[72:73]
	s_nop 0
	v_mul_f32_e32 v31, v19, v27
	v_fma_f32 v34, -v23, v31, v19
	v_fma_f32 v26, v34, v27, v31
	v_div_fixup_f32 v19, v26, v23, v19
	v_rcp_f32_e32 v26, v22
	v_pk_fma_f32 v[42:43], v[58:59], v[42:43], v[46:47]
	v_lshlrev_b32_e32 v34, 16, v48
	v_and_b32_e32 v35, 0xffff0000, v48
	s_nop 0
	v_mul_f32_e32 v30, v18, v26
	v_fma_f32 v31, -v22, v30, v18
	v_fma_f32 v23, v31, v26, v30
	v_div_fixup_f32 v18, v23, v22, v18
	v_lshlrev_b32_e32 v22, 16, v36
	v_and_b32_e32 v23, 0xffff0000, v36
	v_lshlrev_b32_e32 v26, 16, v44
	v_and_b32_e32 v27, 0xffff0000, v44
	v_pk_fma_f32 v[42:43], v[62:63], v[22:23], v[42:43]
	v_lshlrev_b32_e32 v30, 16, v40
	s_waitcnt vmcnt(0)
	v_pk_fma_f32 v[42:43], v[66:67], v[26:27], v[42:43]
	v_and_b32_e32 v31, 0xffff0000, v40
	v_mul_f32_e32 v24, 0xbfb8aa3b, v42
	v_exp_f32_e32 v46, v24
	v_mul_f32_e32 v24, 0xbfb8aa3b, v43
	v_exp_f32_e32 v47, v24
	v_pk_fma_f32 v[38:39], v[54:55], v[22:23], v[38:39]
	v_pk_mul_f32 v[18:19], v[18:19], s[26:27] op_sel_hi:[1,0]
	v_pk_fma_f32 v[38:39], v[58:59], v[26:27], v[38:39]
	v_pk_add_f32 v[46:47], v[46:47], 1.0 op_sel_hi:[1,0]
	v_pk_fma_f32 v[38:39], v[62:63], v[30:31], v[38:39]
	v_rcp_f32_e32 v28, v47
	v_pk_fma_f32 v[38:39], v[66:67], v[34:35], v[38:39]
	s_nop 0
	v_mul_f32_e32 v36, v43, v28
	v_fma_f32 v40, -v47, v36, v43
	v_fma_f32 v24, v40, v28, v36
	v_div_fixup_f32 v43, v24, v47, v43
	v_rcp_f32_e32 v28, v46
	s_nop 0
	s_nop 0
	v_mul_f32_e32 v36, v42, v28
	v_fma_f32 v40, -v46, v36, v42
	v_fma_f32 v24, v40, v28, v36
	v_div_fixup_f32 v42, v24, v46, v42
	v_pk_mul_f32 v[42:43], v[42:43], s[26:27] op_sel_hi:[1,0]
	s_nop 0
	v_cvt_pk_bf16_f32 v24, v42, v43
	v_pk_fma_f32 v[42:43], v[58:59], v[22:23], v[72:73]
	v_pk_fma_f32 v[22:23], v[50:51], v[22:23], 0 op_sel_hi:[1,1,0]
	v_pk_fma_f32 v[42:43], v[62:63], v[26:27], v[42:43]
	v_pk_fma_f32 v[22:23], v[54:55], v[26:27], v[22:23]
	v_pk_fma_f32 v[42:43], v[66:67], v[30:31], v[42:43]
	v_pk_fma_f32 v[22:23], v[58:59], v[30:31], v[22:23]
	v_mul_f32_e32 v28, 0xbfb8aa3b, v42
	v_exp_f32_e32 v46, v28
	v_mul_f32_e32 v28, 0xbfb8aa3b, v43
	v_exp_f32_e32 v47, v28
	v_pk_fma_f32 v[22:23], v[62:63], v[34:35], v[22:23]
	v_lshlrev_b32_e32 v26, 16, v20
	v_and_b32_e32 v27, 0xffff0000, v20
	v_pk_add_f32 v[46:47], v[46:47], 1.0 op_sel_hi:[1,0]
	v_pk_fma_f32 v[22:23], v[66:67], v[26:27], v[22:23]
	v_rcp_f32_e32 v32, v47
	v_mul_f32_e32 v20, 0xbfb8aa3b, v22
	v_exp_f32_e32 v26, v20
	v_mul_f32_e32 v20, 0xbfb8aa3b, v23
	s_nop 0
	v_mul_f32_e32 v40, v43, v32
	v_fma_f32 v44, -v47, v40, v43
	v_fma_f32 v28, v44, v32, v40
	v_div_fixup_f32 v43, v28, v47, v43
	v_rcp_f32_e32 v32, v46
	v_exp_f32_e32 v27, v20
	v_and_b32_e32 v47, 0xffff0000, v25
	v_and_b32_e32 v35, 0xffff0000, v41
	s_nop 0
	v_mul_f32_e32 v40, v42, v32
	v_fma_f32 v44, -v46, v40, v42
	v_fma_f32 v28, v44, v32, v40
	v_div_fixup_f32 v42, v28, v46, v42
	v_pk_mul_f32 v[42:43], v[42:43], s[26:27] op_sel_hi:[1,0]
	v_mul_f32_e32 v32, 0xbfb8aa3b, v38
	v_cvt_pk_bf16_f32 v28, v42, v43
	v_exp_f32_e32 v42, v32
	v_mul_f32_e32 v32, 0xbfb8aa3b, v39
	v_exp_f32_e32 v43, v32
	v_pk_add_f32 v[26:27], v[26:27], 1.0 op_sel_hi:[1,0]
	v_pk_add_f32 v[42:43], v[42:43], 1.0 op_sel_hi:[1,0]
	s_nop 0
	v_rcp_f32_e32 v36, v43
	v_rcp_f32_e32 v30, v27
	s_nop 0
	v_mul_f32_e32 v44, v39, v36
	v_fma_f32 v46, -v43, v44, v39
	v_fma_f32 v32, v46, v36, v44
	v_div_fixup_f32 v39, v32, v43, v39
	v_rcp_f32_e32 v36, v42
	s_nop 0
	v_lshlrev_b32_e32 v46, 16, v25
	s_nop 0
	v_mul_f32_e32 v43, v38, v36
	v_fma_f32 v44, -v42, v43, v38
	v_fma_f32 v32, v44, v36, v43
	v_div_fixup_f32 v38, v32, v42, v38
	v_mul_f32_e32 v32, v23, v30
	v_fma_f32 v34, -v27, v32, v23
	v_fma_f32 v20, v34, v30, v32
	v_div_fixup_f32 v23, v20, v27, v23
	v_rcp_f32_e32 v27, v26
	v_lshlrev_b32_e32 v42, 16, v29
	v_and_b32_e32 v43, 0xffff0000, v29
	v_pk_fma_f32 v[46:47], v[52:53], v[46:47], 0 op_sel_hi:[1,1,0]
	s_nop 0
	v_mul_f32_e32 v31, v22, v27
	v_fma_f32 v32, -v26, v31, v22
	v_fma_f32 v20, v32, v27, v31
	v_lshlrev_b32_e32 v30, 16, v45
	v_and_b32_e32 v31, 0xffff0000, v45
	v_lshlrev_b32_e32 v34, 16, v41
	v_lshlrev_b32_e32 v40, 16, v33
	v_and_b32_e32 v41, 0xffff0000, v33
	v_pk_fma_f32 v[44:45], v[52:53], v[42:43], 0 op_sel_hi:[1,1,0]
	v_pk_fma_f32 v[42:43], v[56:57], v[42:43], v[46:47]
	v_div_fixup_f32 v22, v20, v26, v22
	v_lshlrev_b32_e32 v26, 16, v37
	v_and_b32_e32 v27, 0xffff0000, v37
	v_pk_fma_f32 v[32:33], v[52:53], v[40:41], 0 op_sel_hi:[1,1,0]
	v_pk_fma_f32 v[44:45], v[56:57], v[40:41], v[44:45]
	v_pk_fma_f32 v[40:41], v[60:61], v[40:41], v[42:43]
	v_pk_mul_f32 v[38:39], v[38:39], s[26:27] op_sel_hi:[1,0]
	v_pk_fma_f32 v[40:41], v[64:65], v[26:27], v[40:41]
	v_cvt_pk_bf16_f32 v38, v38, v39
	v_pk_fma_f32 v[40:41], v[68:69], v[30:31], v[40:41]
	v_pk_fma_f32 v[32:33], v[56:57], v[26:27], v[32:33]
	v_mul_f32_e32 v20, 0xbfb8aa3b, v40
	v_exp_f32_e32 v42, v20
	v_mul_f32_e32 v20, 0xbfb8aa3b, v41
	v_exp_f32_e32 v43, v20
	v_pk_fma_f32 v[32:33], v[60:61], v[30:31], v[32:33]
	v_lshlrev_b32_e32 v36, 16, v49
	v_and_b32_e32 v37, 0xffff0000, v49
	v_pk_add_f32 v[42:43], v[42:43], 1.0 op_sel_hi:[1,0]
	v_pk_fma_f32 v[32:33], v[64:65], v[34:35], v[32:33]
	v_rcp_f32_e32 v25, v43
	v_pk_fma_f32 v[32:33], v[68:69], v[36:37], v[32:33]
	v_pk_mul_f32 v[22:23], v[22:23], s[26:27] op_sel_hi:[1,0]
	s_nop 0
	v_mul_f32_e32 v39, v41, v25
	v_fma_f32 v46, -v43, v39, v41
	v_fma_f32 v20, v46, v25, v39
	v_div_fixup_f32 v41, v20, v43, v41
	v_rcp_f32_e32 v25, v42
	s_nop 0
	s_nop 0
	v_mul_f32_e32 v39, v40, v25
	v_fma_f32 v43, -v42, v39, v40
	v_fma_f32 v20, v43, v25, v39
	v_div_fixup_f32 v40, v20, v42, v40
	v_pk_mul_f32 v[40:41], v[40:41], s[26:27] op_sel_hi:[1,0]
	s_nop 0
	v_cvt_pk_bf16_f32 v25, v40, v41
	v_pk_fma_f32 v[40:41], v[60:61], v[26:27], v[44:45]
	v_pk_fma_f32 v[26:27], v[52:53], v[26:27], 0 op_sel_hi:[1,1,0]
	v_pk_fma_f32 v[40:41], v[64:65], v[30:31], v[40:41]
	v_pk_fma_f32 v[26:27], v[56:57], v[30:31], v[26:27]
	v_pk_fma_f32 v[40:41], v[68:69], v[34:35], v[40:41]
	v_pk_fma_f32 v[26:27], v[60:61], v[34:35], v[26:27]
	v_mul_f32_e32 v20, 0xbfb8aa3b, v40
	v_exp_f32_e32 v42, v20
	v_mul_f32_e32 v20, 0xbfb8aa3b, v41
	v_exp_f32_e32 v43, v20
	v_pk_fma_f32 v[26:27], v[64:65], v[36:37], v[26:27]
	v_pk_add_f32 v[42:43], v[42:43], 1.0 op_sel_hi:[1,0]
	s_nop 0
	v_rcp_f32_e32 v29, v43
	s_nop 0
	s_nop 0
	v_mul_f32_e32 v44, v41, v29
	v_fma_f32 v45, -v43, v44, v41
	v_fma_f32 v20, v45, v29, v44
	v_div_fixup_f32 v41, v20, v43, v41
	v_rcp_f32_e32 v29, v42
	s_nop 0
	s_nop 0
	v_mul_f32_e32 v43, v40, v29
	v_fma_f32 v44, -v42, v43, v40
	v_fma_f32 v20, v44, v29, v43
	v_div_fixup_f32 v40, v20, v42, v40
	v_pk_mul_f32 v[40:41], v[40:41], s[26:27] op_sel_hi:[1,0]
	v_mul_f32_e32 v20, 0xbfb8aa3b, v32
	v_cvt_pk_bf16_f32 v29, v40, v41
	v_exp_f32_e32 v40, v20
	v_mul_f32_e32 v20, 0xbfb8aa3b, v33
	v_exp_f32_e32 v41, v20
	s_nop 0
	v_pk_add_f32 v[40:41], v[40:41], 1.0 op_sel_hi:[1,0]
	s_nop 0
	v_rcp_f32_e32 v39, v41
	s_nop 0
	s_nop 0
	v_mul_f32_e32 v43, v33, v39
	v_fma_f32 v44, -v41, v43, v33
	v_fma_f32 v20, v44, v39, v43
	v_div_fixup_f32 v33, v20, v41, v33
	v_rcp_f32_e32 v39, v40
	s_nop 0
	s_nop 0
	v_mul_f32_e32 v42, v32, v39
	v_fma_f32 v43, -v40, v42, v32
	v_fma_f32 v20, v43, v39, v42
	v_div_fixup_f32 v32, v20, v40, v32
	v_lshlrev_b32_e32 v20, 16, v21
	v_and_b32_e32 v21, 0xffff0000, v21
	v_pk_fma_f32 v[20:21], v[68:69], v[20:21], v[26:27]
	v_pk_mul_f32 v[32:33], v[32:33], s[26:27] op_sel_hi:[1,0]
	v_mul_f32_e32 v26, 0xbfb8aa3b, v20
	v_mul_f32_e32 v27, 0xbfb8aa3b, v21
	v_exp_f32_e32 v26, v26
	v_exp_f32_e32 v27, v27
	v_cvt_pk_bf16_f32 v32, v32, v33
	v_lshlrev_b32_e32 v40, 2, v102
	v_pk_add_f32 v[26:27], v[26:27], 1.0 op_sel_hi:[1,0]
	s_nop 0
	v_rcp_f32_e32 v31, v27
	s_nop 0
	s_nop 0
	v_mul_f32_e32 v34, v21, v31
	v_fma_f32 v35, -v27, v34, v21
	v_fma_f32 v30, v35, v31, v34
	v_div_fixup_f32 v21, v30, v27, v21
	v_rcp_f32_e32 v30, v26
	s_add_i32 s0, 0, 0x10000
	s_add_i32 s1, 0, 0x18800
	s_nop 0
	v_mul_f32_e32 v33, v20, v30
	v_fma_f32 v34, -v26, v33, v20
	v_fma_f32 v27, v34, v30, v33
	v_div_fixup_f32 v20, v27, v26, v20
	v_cvt_pk_bf16_f32 v33, v18, v19
	v_and_b32_e32 v18, 48, v101
	v_lshlrev_b32_e32 v19, 1, v101
	v_pk_mul_f32 v[20:21], v[20:21], s[26:27] op_sel_hi:[1,0]
	v_and_or_b32 v18, v19, 8, v18
	v_cvt_pk_bf16_f32 v35, v20, v21
	v_lshrrev_b32_e32 v18, 1, v18
	v_lshrrev_b32_e32 v19, 5, v103
	v_lshlrev_b32_e32 v20, 6, v100
	v_or_b32_e32 v18, v18, v19
	v_and_b32_e32 v36, 0xffffc000, v20
	v_lshlrev_b32_e32 v20, 5, v101
	v_lshlrev_b32_e32 v18, 9, v18
	v_and_b32_e32 v19, 48, v178
	v_and_b32_e32 v20, 0x100, v20
	v_or3_b32 v37, v18, v19, v20
	v_add3_u32 v39, s0, v36, v37
	ds_write_b128 v39, v[14:17]
	v_add_u32_e32 v14, s1, v40
	v_cvt_pk_bf16_f32 v34, v22, v23
	ds_read_b32 v22, v14
	v_add_u32_e32 v14, s8, v40
	ds_read_b32 v26, v14
	v_cvt_pk_bf16_f32 v27, v70, v71
	v_lshlrev_b32_e32 v16, 16, v105
	v_and_b32_e32 v17, 0xffff0000, v105
	v_lshlrev_b32_e32 v20, 16, v74
	v_and_b32_e32 v21, 0xffff0000, v74
	s_waitcnt lgkmcnt(1)
	v_pk_mul_f32 v[14:15], v[22:23], v[16:17] op_sel_hi:[0,1]
	s_waitcnt lgkmcnt(0)
	v_pk_mul_f32 v[16:17], v[26:27], v[16:17] op_sel_hi:[0,1]
	v_cvt_pk_bf16_f32 v18, v16, v17
	v_pk_mul_f32 v[16:17], v[22:23], v[20:21] op_sel_hi:[0,1]
	v_lshlrev_b32_e32 v30, 16, v24
	v_and_b32_e32 v31, 0xffff0000, v24
	v_lshlrev_b32_e32 v24, 16, v25
	v_and_b32_e32 v25, 0xffff0000, v25
	v_cvt_pk_bf16_f32 v14, v14, v15
	v_cvt_pk_bf16_f32 v15, v16, v17
	v_pk_mul_f32 v[16:17], v[26:27], v[20:21] op_sel_hi:[0,1]
	v_cvt_pk_bf16_f32 v19, v16, v17
	v_pk_mul_f32 v[16:17], v[22:23], v[30:31] op_sel_hi:[0,1]
	v_pk_mul_f32 v[22:23], v[22:23], v[24:25] op_sel_hi:[0,1]
	v_cvt_pk_bf16_f32 v16, v16, v17
	v_pk_mul_f32 v[20:21], v[26:27], v[30:31] op_sel_hi:[0,1]
	v_cvt_pk_bf16_f32 v17, v22, v23
	v_pk_mul_f32 v[22:23], v[26:27], v[24:25] op_sel_hi:[0,1]
	v_add3_u32 v26, 0, v36, v37
	v_cvt_pk_bf16_f32 v20, v20, v21
	v_cvt_pk_bf16_f32 v21, v22, v23
	ds_write_b128 v26, v[14:17]
	ds_write_b128 v26, v[18:21] offset:32768
	ds_write_b128 v39, v[10:13] offset:64
	v_or_b32_e32 v10, 4, v40
	v_add_u32_e32 v11, s1, v10
	v_add_u32_e32 v10, s8, v10
	ds_read_b32 v18, v11
	ds_read_b32 v20, v10
	v_lshlrev_b32_e32 v12, 16, v106
	v_and_b32_e32 v13, 0xffff0000, v106
	v_lshlrev_b32_e32 v16, 16, v75
	v_and_b32_e32 v17, 0xffff0000, v75
	s_waitcnt lgkmcnt(1)
	v_pk_mul_f32 v[10:11], v[18:19], v[12:13] op_sel_hi:[0,1]
	s_waitcnt lgkmcnt(0)
	v_pk_mul_f32 v[12:13], v[20:21], v[12:13] op_sel_hi:[0,1]
	v_cvt_pk_bf16_f32 v14, v12, v13
	v_pk_mul_f32 v[12:13], v[18:19], v[16:17] op_sel_hi:[0,1]
	v_lshlrev_b32_e32 v22, 16, v28
	v_and_b32_e32 v23, 0xffff0000, v28
	v_lshlrev_b32_e32 v24, 16, v29
	v_and_b32_e32 v25, 0xffff0000, v29
	v_cvt_pk_bf16_f32 v10, v10, v11
	v_cvt_pk_bf16_f32 v11, v12, v13
	v_pk_mul_f32 v[12:13], v[20:21], v[16:17] op_sel_hi:[0,1]
	v_cvt_pk_bf16_f32 v15, v12, v13
	v_pk_mul_f32 v[12:13], v[18:19], v[22:23] op_sel_hi:[0,1]
	v_pk_mul_f32 v[18:19], v[18:19], v[24:25] op_sel_hi:[0,1]
	v_cvt_pk_bf16_f32 v12, v12, v13
	v_pk_mul_f32 v[16:17], v[20:21], v[22:23] op_sel_hi:[0,1]
	v_cvt_pk_bf16_f32 v13, v18, v19
	v_pk_mul_f32 v[18:19], v[20:21], v[24:25] op_sel_hi:[0,1]
	v_cvt_pk_bf16_f32 v16, v16, v17
	v_cvt_pk_bf16_f32 v17, v18, v19
	ds_write_b128 v26, v[10:13] offset:64
	ds_write_b128 v26, v[14:17] offset:32832
	ds_write_b128 v39, v[6:9] offset:128
	v_or_b32_e32 v6, 8, v40
	v_add_u32_e32 v7, s1, v6
	v_add_u32_e32 v6, s8, v6
	ds_read_b32 v14, v7
	ds_read_b32 v16, v6
	v_lshlrev_b32_e32 v8, 16, v98
	v_and_b32_e32 v9, 0xffff0000, v98
	v_lshlrev_b32_e32 v12, 16, v78
	v_and_b32_e32 v13, 0xffff0000, v78
	s_waitcnt lgkmcnt(1)
	v_pk_mul_f32 v[6:7], v[14:15], v[8:9] op_sel_hi:[0,1]
	s_waitcnt lgkmcnt(0)
	v_pk_mul_f32 v[8:9], v[16:17], v[8:9] op_sel_hi:[0,1]
	v_cvt_pk_bf16_f32 v10, v8, v9
	v_pk_mul_f32 v[8:9], v[14:15], v[12:13] op_sel_hi:[0,1]
	v_lshlrev_b32_e32 v18, 16, v38
	v_and_b32_e32 v19, 0xffff0000, v38
	v_lshlrev_b32_e32 v20, 16, v32
	v_and_b32_e32 v21, 0xffff0000, v32
	v_cvt_pk_bf16_f32 v6, v6, v7
	v_cvt_pk_bf16_f32 v7, v8, v9
	v_pk_mul_f32 v[8:9], v[16:17], v[12:13] op_sel_hi:[0,1]
	v_cvt_pk_bf16_f32 v11, v8, v9
	v_pk_mul_f32 v[8:9], v[14:15], v[18:19] op_sel_hi:[0,1]
	v_pk_mul_f32 v[14:15], v[14:15], v[20:21] op_sel_hi:[0,1]
	v_cvt_pk_bf16_f32 v8, v8, v9
	v_pk_mul_f32 v[12:13], v[16:17], v[18:19] op_sel_hi:[0,1]
	v_cvt_pk_bf16_f32 v9, v14, v15
	v_pk_mul_f32 v[14:15], v[16:17], v[20:21] op_sel_hi:[0,1]
	v_cvt_pk_bf16_f32 v12, v12, v13
	v_cvt_pk_bf16_f32 v13, v14, v15
	ds_write_b128 v26, v[6:9] offset:128
	ds_write_b128 v26, v[10:13] offset:32896
	ds_write_b128 v39, v[2:5] offset:192
	v_lshl_or_b32 v2, v101, 2, 12
	v_add_u32_e32 v3, s1, v2
	v_add_u32_e32 v2, s8, v2
	ds_read_b32 v10, v3
	ds_read_b32 v12, v2
	v_lshlrev_b32_e32 v4, 16, v27
	v_and_b32_e32 v5, 0xffff0000, v27
	v_lshlrev_b32_e32 v8, 16, v33
	v_and_b32_e32 v9, 0xffff0000, v33
	s_waitcnt lgkmcnt(1)
	v_pk_mul_f32 v[2:3], v[10:11], v[4:5] op_sel_hi:[0,1]
	s_waitcnt lgkmcnt(0)
	v_pk_mul_f32 v[4:5], v[12:13], v[4:5] op_sel_hi:[0,1]
	v_cvt_pk_bf16_f32 v6, v4, v5
	v_pk_mul_f32 v[4:5], v[10:11], v[8:9] op_sel_hi:[0,1]
	v_lshlrev_b32_e32 v14, 16, v34
	v_and_b32_e32 v15, 0xffff0000, v34
	v_lshlrev_b32_e32 v16, 16, v35
	v_and_b32_e32 v17, 0xffff0000, v35
	v_cvt_pk_bf16_f32 v2, v2, v3
	v_cvt_pk_bf16_f32 v3, v4, v5
	v_pk_mul_f32 v[4:5], v[12:13], v[8:9] op_sel_hi:[0,1]
	v_cvt_pk_bf16_f32 v7, v4, v5
	v_pk_mul_f32 v[4:5], v[10:11], v[14:15] op_sel_hi:[0,1]
	v_pk_mul_f32 v[10:11], v[10:11], v[16:17] op_sel_hi:[0,1]
	v_cvt_pk_bf16_f32 v4, v4, v5
	v_pk_mul_f32 v[8:9], v[12:13], v[14:15] op_sel_hi:[0,1]
	v_cvt_pk_bf16_f32 v5, v10, v11
	v_pk_mul_f32 v[10:11], v[12:13], v[16:17] op_sel_hi:[0,1]
	v_cvt_pk_bf16_f32 v8, v8, v9
	v_cvt_pk_bf16_f32 v9, v10, v11
	ds_write_b128 v26, v[2:5] offset:192
	ds_write_b128 v26, v[6:9] offset:32960
	v_lshlrev_b32_e32 v2, 4, v104
	s_lshl_b32 s1, s5, 15
	v_lshlrev_b32_e32 v78, 3, v104
	v_and_b32_e32 v2, 0xc0, v2
	v_lshlrev_b32_e32 v3, 1, v104
	s_add_i32 s1, s1, 0
	s_lshl_b32 s8, s4, 9
	v_and_or_b32 v2, v78, 24, v2
	v_and_b32_e32 v3, 32, v3
	v_and_b32_e32 v4, 0x100, v78
	s_add_i32 s1, s1, s8
	v_or3_b32 v79, v2, v3, v4
	s_waitcnt lgkmcnt(0)
	s_barrier
	v_add_u32_e32 v92, s1, v79
	ds_read_b64_tr_b16 v[2:3], v92 offset:0
	ds_read_b64_tr_b16 v[4:5], v92 offset:0x800
	ds_read_b64_tr_b16 v[66:67], v92 offset:0x1000
	ds_read_b64_tr_b16 v[68:69], v92 offset:0x1800
	ds_read_b64_tr_b16 v[70:71], v92 offset:0x2000
	ds_read_b64_tr_b16 v[72:73], v92 offset:0x2800
	ds_read_b64_tr_b16 v[74:75], v92 offset:0x3000
	ds_read_b64_tr_b16 v[76:77], v92 offset:0x3800
	v_add_u32_e32 v93, s0, v79
	s_waitcnt lgkmcnt(0)
	ds_read_b64_tr_b16 v[6:7], v93 offset:0
	ds_read_b64_tr_b16 v[8:9], v93 offset:0x800
	ds_read_b64_tr_b16 v[10:11], v93 offset:0x1000
	ds_read_b64_tr_b16 v[12:13], v93 offset:0x1800
	ds_read_b64_tr_b16 v[14:15], v93 offset:0x2000
	ds_read_b64_tr_b16 v[16:17], v93 offset:0x2800
	ds_read_b64_tr_b16 v[18:19], v93 offset:0x3000
	ds_read_b64_tr_b16 v[20:21], v93 offset:0x3800
	s_nop 0
	s_waitcnt lgkmcnt(6)
	s_add_i32 s0, 0, 0x14000
	v_mfma_f32_32x32x16_bf16 v[50:65], v[2:5], v[6:9], 0
	ds_read_b64_tr_b16 v[6:7], v93 offset:0x200
	ds_read_b64_tr_b16 v[8:9], v93 offset:0xa00
	s_waitcnt lgkmcnt(6)
	v_add_u32_e32 v79, s0, v79
	s_movk_i32 s0, 0xff
	v_cmp_lt_i32_e32 vcc, s0, v100
	v_mfma_f32_32x32x16_bf16 v[50:65], v[66:69], v[10:13], v[50:65]
	ds_read_b64_tr_b16 v[10:11], v93 offset:0x1200
	ds_read_b64_tr_b16 v[12:13], v93 offset:0x1a00
	s_waitcnt lgkmcnt(6)
	s_nop 0
	v_mfma_f32_32x32x16_bf16 v[50:65], v[70:73], v[14:17], v[50:65]
	ds_read_b64_tr_b16 v[14:15], v93 offset:0x2200
	ds_read_b64_tr_b16 v[16:17], v93 offset:0x2a00
	s_waitcnt lgkmcnt(6)
	s_nop 0
	v_mfma_f32_32x32x16_bf16 v[50:65], v[74:77], v[18:21], v[50:65]
	ds_read_b64_tr_b16 v[18:19], v93 offset:0x3200
	ds_read_b64_tr_b16 v[20:21], v93 offset:0x3a00
	s_waitcnt lgkmcnt(6)
	s_nop 0
	v_mfma_f32_32x32x16_bf16 v[34:49], v[2:5], v[6:9], 0
	ds_read_b64_tr_b16 v[6:7], v93 offset:0x400
	ds_read_b64_tr_b16 v[8:9], v93 offset:0xc00
	s_waitcnt lgkmcnt(6)
	s_nop 0
	v_mfma_f32_32x32x16_bf16 v[34:49], v[66:69], v[10:13], v[34:49]
	ds_read_b64_tr_b16 v[10:11], v93 offset:0x1400
	ds_read_b64_tr_b16 v[12:13], v93 offset:0x1c00
	s_waitcnt lgkmcnt(6)
	s_nop 0
	v_mfma_f32_32x32x16_bf16 v[34:49], v[70:73], v[14:17], v[34:49]
	ds_read_b64_tr_b16 v[14:15], v93 offset:0x2400
	ds_read_b64_tr_b16 v[16:17], v93 offset:0x2c00
	s_waitcnt lgkmcnt(6)
	ds_read_b64_tr_b16 v[80:81], v93 offset:0x3400
	ds_read_b64_tr_b16 v[82:83], v93 offset:0x3c00
	s_waitcnt lgkmcnt(6)
	s_nop 0
	v_mfma_f32_32x32x16_bf16 v[34:49], v[74:77], v[18:21], v[34:49]
	v_mfma_f32_32x32x16_bf16 v[18:33], v[2:5], v[6:9], 0
	ds_read_b64_tr_b16 v[6:7], v93 offset:0x600
	ds_read_b64_tr_b16 v[8:9], v93 offset:0xe00
	s_waitcnt lgkmcnt(6)
	ds_read_b64_tr_b16 v[84:85], v93 offset:0x1600
	ds_read_b64_tr_b16 v[86:87], v93 offset:0x1e00
	s_waitcnt lgkmcnt(6)
	ds_read_b64_tr_b16 v[88:89], v93 offset:0x2600
	ds_read_b64_tr_b16 v[90:91], v93 offset:0x2e00
	s_nop 0
	v_mfma_f32_32x32x16_bf16 v[18:33], v[66:69], v[10:13], v[18:33]
	s_waitcnt lgkmcnt(6)
	v_mfma_f32_32x32x16_bf16 v[18:33], v[70:73], v[14:17], v[18:33]
	v_mfma_f32_32x32x16_bf16 v[18:33], v[74:77], v[80:83], v[18:33]
	ds_read_b64_tr_b16 v[80:81], v93 offset:0x3600
	ds_read_b64_tr_b16 v[82:83], v93 offset:0x3e00
	s_waitcnt lgkmcnt(6)
	s_waitcnt lgkmcnt(4)
	s_waitcnt lgkmcnt(2)
	s_nop 0
	s_waitcnt lgkmcnt(0)
	v_mfma_f32_32x32x16_bf16 v[2:17], v[2:5], v[6:9], 0
	v_mfma_f32_32x32x16_bf16 v[2:17], v[66:69], v[84:87], v[2:17]
	v_add_u32_e32 v84, 0x4000, v92
	ds_read_b64_tr_b16 v[66:67], v84 offset:0
	ds_read_b64_tr_b16 v[68:69], v84 offset:0x800
	v_mfma_f32_32x32x16_bf16 v[2:17], v[70:73], v[88:91], v[2:17]
	ds_read_b64_tr_b16 v[70:71], v84 offset:0x1000
	ds_read_b64_tr_b16 v[72:73], v84 offset:0x1800
	v_mfma_f32_32x32x16_bf16 v[2:17], v[74:77], v[80:83], v[2:17]
	ds_read_b64_tr_b16 v[74:75], v84 offset:0x2000
	ds_read_b64_tr_b16 v[76:77], v84 offset:0x2800
	ds_read_b64_tr_b16 v[80:81], v84 offset:0x3000
	ds_read_b64_tr_b16 v[82:83], v84 offset:0x3800
	s_nop 0
	s_waitcnt lgkmcnt(0)
	ds_read_b64_tr_b16 v[84:85], v79 offset:0
	ds_read_b64_tr_b16 v[86:87], v79 offset:0x800
	ds_read_b64_tr_b16 v[88:89], v79 offset:0x1000
	ds_read_b64_tr_b16 v[90:91], v79 offset:0x1800
	ds_read_b64_tr_b16 v[92:93], v79 offset:0x2000
	ds_read_b64_tr_b16 v[94:95], v79 offset:0x2800
	ds_read_b64_tr_b16 v[96:97], v79 offset:0x3000
	ds_read_b64_tr_b16 v[98:99], v79 offset:0x3800
	s_nop 0
	s_waitcnt lgkmcnt(6)
	s_nop 0
	v_mfma_f32_32x32x16_bf16 v[50:65], v[66:69], v[84:87], v[50:65]
	ds_read_b64_tr_b16 v[84:85], v79 offset:0x200
	ds_read_b64_tr_b16 v[86:87], v79 offset:0xa00
	s_waitcnt lgkmcnt(6)
	s_nop 0
	v_mfma_f32_32x32x16_bf16 v[50:65], v[70:73], v[88:91], v[50:65]
	ds_read_b64_tr_b16 v[88:89], v79 offset:0x1200
	ds_read_b64_tr_b16 v[90:91], v79 offset:0x1a00
	s_waitcnt lgkmcnt(6)
	s_nop 0
	v_mfma_f32_32x32x16_bf16 v[50:65], v[74:77], v[92:95], v[50:65]
	ds_read_b64_tr_b16 v[92:93], v79 offset:0x2200
	ds_read_b64_tr_b16 v[94:95], v79 offset:0x2a00
	s_waitcnt lgkmcnt(6)
	s_nop 0
	v_mfma_f32_32x32x16_bf16 v[50:65], v[80:83], v[96:99], v[50:65]
	ds_read_b64_tr_b16 v[96:97], v79 offset:0x3200
	ds_read_b64_tr_b16 v[98:99], v79 offset:0x3a00
	s_waitcnt lgkmcnt(6)
	s_nop 0
	v_mfma_f32_32x32x16_bf16 v[34:49], v[66:69], v[84:87], v[34:49]
	ds_read_b64_tr_b16 v[84:85], v79 offset:0x400
	ds_read_b64_tr_b16 v[86:87], v79 offset:0xc00
	s_waitcnt lgkmcnt(6)
	s_nop 0
	v_mfma_f32_32x32x16_bf16 v[34:49], v[70:73], v[88:91], v[34:49]
	ds_read_b64_tr_b16 v[88:89], v79 offset:0x1400
	ds_read_b64_tr_b16 v[90:91], v79 offset:0x1c00
	s_waitcnt lgkmcnt(6)
	s_nop 0
	v_mfma_f32_32x32x16_bf16 v[34:49], v[74:77], v[92:95], v[34:49]
	ds_read_b64_tr_b16 v[92:93], v79 offset:0x2400
	ds_read_b64_tr_b16 v[94:95], v79 offset:0x2c00
	s_waitcnt lgkmcnt(6)
	s_nop 0
	v_mfma_f32_32x32x16_bf16 v[34:49], v[80:83], v[96:99], v[34:49]
	ds_read_b64_tr_b16 v[96:97], v79 offset:0x3400
	ds_read_b64_tr_b16 v[98:99], v79 offset:0x3c00
	s_waitcnt lgkmcnt(6)
	s_nop 0
	v_mfma_f32_32x32x16_bf16 v[18:33], v[66:69], v[84:87], v[18:33]
	ds_read_b64_tr_b16 v[84:85], v79 offset:0x600
	ds_read_b64_tr_b16 v[86:87], v79 offset:0xe00
	s_waitcnt lgkmcnt(6)
	s_nop 0
	v_mfma_f32_32x32x16_bf16 v[18:33], v[70:73], v[88:91], v[18:33]
	ds_read_b64_tr_b16 v[88:89], v79 offset:0x1600
	ds_read_b64_tr_b16 v[90:91], v79 offset:0x1e00
	s_waitcnt lgkmcnt(6)
	s_nop 0
	v_mfma_f32_32x32x16_bf16 v[18:33], v[74:77], v[92:95], v[18:33]
	ds_read_b64_tr_b16 v[92:93], v79 offset:0x2600
	ds_read_b64_tr_b16 v[94:95], v79 offset:0x2e00
	s_waitcnt lgkmcnt(6)
	s_nop 0
	v_mfma_f32_32x32x16_bf16 v[18:33], v[80:83], v[96:99], v[18:33]
	ds_read_b64_tr_b16 v[96:97], v79 offset:0x3600
	ds_read_b64_tr_b16 v[98:99], v79 offset:0x3e00
	s_waitcnt lgkmcnt(6)
	s_waitcnt lgkmcnt(4)
	s_waitcnt lgkmcnt(2)
	v_ashrrev_i32_e32 v79, 7, v100
	s_waitcnt lgkmcnt(0)
	v_mfma_f32_32x32x16_bf16 v[2:17], v[66:69], v[84:87], v[2:17]
	v_lshlrev_b32_e32 v66, 7, v100
	v_lshlrev_b32_e32 v67, 14, v79
	v_and_b32_e32 v66, 0xffff8000, v66
	v_and_b32_e32 v67, 0x4000, v67
	v_add3_u32 v66, 0, v66, v67
	v_lshlrev_b32_e32 v67, 1, v100
	v_lshlrev_b32_e32 v68, 4, v100
	v_mfma_f32_32x32x16_bf16 v[2:17], v[70:73], v[88:91], v[2:17]
	v_and_b32_e32 v67, 62, v67
	v_and_b32_e32 v68, 0x600, v68
	v_mfma_f32_32x32x16_bf16 v[2:17], v[74:77], v[92:95], v[2:17]
	v_mfma_f32_32x32x16_bf16 v[2:17], v[80:83], v[96:99], v[2:17]
	v_add3_u32 v80, v66, v68, v67
	ds_read_u16 v66, v80 offset:6144
	ds_read_u16 v67, v80 offset:6272
	ds_read_u16 v68, v80 offset:6208
	ds_read_u16 v69, v80 offset:6336
	ds_read_u16 v70, v80 offset:4352
	ds_read_u16 v71, v80 offset:4416
	ds_read_u16 v73, v80 offset:4544
	s_waitcnt lgkmcnt(5)
	v_lshlrev_b32_e32 v67, 16, v67
	v_lshlrev_b32_e32 v66, 16, v66
	s_waitcnt lgkmcnt(3)
	v_lshlrev_b32_e32 v69, 16, v69
	s_waitcnt lgkmcnt(1)
	v_lshlrev_b32_e32 v72, 16, v71
	ds_read_u16 v71, v80 offset:4480
	ds_read_u16 v81, v80 offset:6400
	ds_read_u16 v88, v80 offset:6464
	ds_read_u16 v89, v80 offset:6528
	ds_read_u16 v90, v80 offset:6592
	ds_read_u16 v74, v80
	ds_read_u16 v75, v80 offset:128
	ds_read_u16 v76, v80 offset:2048
	ds_read_u16 v77, v80 offset:2176
	ds_read_u16 v82, v80 offset:256
	ds_read_u16 v83, v80 offset:384
	ds_read_u16 v84, v80 offset:2304
	ds_read_u16 v85, v80 offset:2432
	s_waitcnt lgkmcnt(7)
	v_lshlrev_b32_e32 v74, 16, v74
	s_waitcnt lgkmcnt(6)
	v_lshlrev_b32_e32 v75, 16, v75
	s_waitcnt lgkmcnt(4)
	v_lshlrev_b32_e32 v77, 16, v77
	v_lshlrev_b32_e32 v76, 16, v76
	v_pk_add_f32 v[74:75], v[74:75], 0 op_sel_hi:[1,0]
	s_waitcnt lgkmcnt(2)
	v_lshlrev_b32_e32 v83, 16, v83
	v_pk_add_f32 v[74:75], v[74:75], v[76:77]
	ds_read_u16 v76, v80 offset:4096
	ds_read_u16 v77, v80 offset:4224
	v_lshlrev_b32_e32 v82, 16, v82
	s_waitcnt lgkmcnt(2)
	v_lshlrev_b32_e32 v85, 16, v85
	v_lshlrev_b32_e32 v84, 16, v84
	v_pk_add_f32 v[74:75], v[74:75], v[82:83]
	s_waitcnt lgkmcnt(0)
	v_lshlrev_b32_e32 v77, 16, v77
	v_pk_add_f32 v[74:75], v[74:75], v[84:85]
	v_lshlrev_b32_e32 v76, 16, v76
	v_pk_add_f32 v[74:75], v[74:75], v[76:77]
	ds_read_u16 v76, v80 offset:64
	ds_read_u16 v77, v80 offset:192
	ds_read_u16 v82, v80 offset:2112
	ds_read_u16 v83, v80 offset:2240
	ds_read_u16 v84, v80 offset:320
	ds_read_u16 v85, v80 offset:448
	ds_read_u16 v86, v80 offset:2368
	ds_read_u16 v87, v80 offset:2496
	s_waitcnt lgkmcnt(7)
	v_lshlrev_b32_e32 v76, 16, v76
	s_waitcnt lgkmcnt(6)
	v_lshlrev_b32_e32 v77, 16, v77
	s_waitcnt lgkmcnt(4)
	v_lshlrev_b32_e32 v83, 16, v83
	v_lshlrev_b32_e32 v82, 16, v82
	v_pk_add_f32 v[76:77], v[76:77], 0 op_sel_hi:[1,0]
	s_waitcnt lgkmcnt(2)
	v_lshlrev_b32_e32 v85, 16, v85
	v_pk_add_f32 v[76:77], v[76:77], v[82:83]
	ds_read_u16 v82, v80 offset:4160
	ds_read_u16 v83, v80 offset:4288
	v_lshlrev_b32_e32 v84, 16, v84
	s_waitcnt lgkmcnt(2)
	v_lshlrev_b32_e32 v87, 16, v87
	v_lshlrev_b32_e32 v86, 16, v86
	v_pk_add_f32 v[76:77], v[76:77], v[84:85]
	s_waitcnt lgkmcnt(0)
	v_lshlrev_b32_e32 v83, 16, v83
	v_pk_add_f32 v[76:77], v[76:77], v[86:87]
	v_lshlrev_b32_e32 v82, 16, v82
	v_lshlrev_b32_e32 v68, 16, v68
	v_lshlrev_b32_e32 v70, 16, v70
	v_lshlrev_b32_e32 v71, 16, v71
	v_pk_add_f32 v[76:77], v[76:77], v[82:83]
	v_pk_add_f32 v[66:67], v[74:75], v[66:67]
	v_lshlrev_b32_e32 v73, 16, v73
	v_lshlrev_b32_e32 v83, 16, v89
	v_lshlrev_b32_e32 v82, 16, v81
	v_pk_add_f32 v[68:69], v[76:77], v[68:69]
	v_pk_add_f32 v[66:67], v[66:67], v[70:71]
	v_pk_add_f32 v[68:69], v[68:69], v[72:73]
	v_pk_add_f32 v[66:67], v[66:67], v[82:83]
	ds_read_u16 v70, v80 offset:8192
	ds_read_u16 v71, v80 offset:8320
	ds_read_u16 v72, v80 offset:8256
	ds_read_u16 v73, v80 offset:8384
	ds_read_u16 v74, v80 offset:10240
	ds_read_u16 v75, v80 offset:10368
	ds_read_u16 v76, v80 offset:10304
	ds_read_u16 v77, v80 offset:10432
	ds_read_u16 v81, v80 offset:8448
	ds_read_u16 v82, v80 offset:8576
	v_lshlrev_b32_e32 v85, 16, v90
	v_lshlrev_b32_e32 v84, 16, v88
	v_pk_add_f32 v[68:69], v[68:69], v[84:85]
	s_waitcnt lgkmcnt(8)
	v_lshlrev_b32_e32 v71, 16, v71
	s_waitcnt lgkmcnt(0)
	v_lshlrev_b32_e32 v83, 16, v82
	v_lshlrev_b32_e32 v82, 16, v81
	ds_read_u16 v81, v80 offset:8512
	ds_read_u16 v84, v80 offset:8640
	v_lshlrev_b32_e32 v70, 16, v70
	v_lshlrev_b32_e32 v73, 16, v73
	v_lshlrev_b32_e32 v72, 16, v72
	v_lshlrev_b32_e32 v75, 16, v75
	s_waitcnt lgkmcnt(0)
	v_lshlrev_b32_e32 v85, 16, v84
	v_lshlrev_b32_e32 v84, 16, v81
	ds_read_u16 v81, v80 offset:10496
	ds_read_u16 v86, v80 offset:10624
	v_lshlrev_b32_e32 v74, 16, v74
	v_pk_add_f32 v[66:67], v[66:67], v[70:71]
	v_lshlrev_b32_e32 v77, 16, v77
	v_lshlrev_b32_e32 v76, 16, v76
	s_waitcnt lgkmcnt(0)
	v_lshlrev_b32_e32 v87, 16, v86
	v_lshlrev_b32_e32 v86, 16, v81
	ds_read_u16 v81, v80 offset:10560
	ds_read_u16 v88, v80 offset:10688
	v_pk_add_f32 v[68:69], v[68:69], v[72:73]
	v_pk_add_f32 v[66:67], v[66:67], v[74:75]
	v_pk_add_f32 v[68:69], v[68:69], v[76:77]
	v_pk_add_f32 v[66:67], v[66:67], v[82:83]
	s_waitcnt lgkmcnt(0)
	v_lshlrev_b32_e32 v89, 16, v88
	v_lshlrev_b32_e32 v88, 16, v81
	ds_read_u16 v70, v80 offset:12288
	ds_read_u16 v71, v80 offset:12416
	ds_read_u16 v72, v80 offset:12352
	ds_read_u16 v73, v80 offset:12480
	ds_read_u16 v74, v80 offset:14336
	ds_read_u16 v75, v80 offset:14464
	ds_read_u16 v76, v80 offset:14400
	ds_read_u16 v77, v80 offset:14528
	ds_read_u16 v81, v80 offset:12544
	ds_read_u16 v82, v80 offset:12672
	v_pk_add_f32 v[68:69], v[68:69], v[84:85]
	v_pk_add_f32 v[66:67], v[66:67], v[86:87]
	v_pk_add_f32 v[68:69], v[68:69], v[88:89]
	s_waitcnt lgkmcnt(8)
	v_lshlrev_b32_e32 v71, 16, v71
	s_waitcnt lgkmcnt(0)
	v_lshlrev_b32_e32 v83, 16, v82
	v_lshlrev_b32_e32 v82, 16, v81
	ds_read_u16 v81, v80 offset:12608
	ds_read_u16 v84, v80 offset:12736
	v_lshlrev_b32_e32 v70, 16, v70
	v_lshlrev_b32_e32 v73, 16, v73
	v_lshlrev_b32_e32 v72, 16, v72
	v_lshlrev_b32_e32 v75, 16, v75
	s_waitcnt lgkmcnt(0)
	v_lshlrev_b32_e32 v85, 16, v84
	v_lshlrev_b32_e32 v84, 16, v81
	ds_read_u16 v81, v80 offset:14592
	ds_read_u16 v86, v80 offset:14720
	ds_read_u16 v88, v80 offset:14656
	ds_read_u16 v80, v80 offset:14784
	v_lshlrev_b32_e32 v74, 16, v74
	v_lshlrev_b32_e32 v77, 16, v77
	v_lshlrev_b32_e32 v76, 16, v76
	v_pk_add_f32 v[66:67], v[66:67], v[70:71]
	v_pk_add_f32 v[68:69], v[68:69], v[72:73]
	v_pk_add_f32 v[66:67], v[66:67], v[74:75]
	v_pk_add_f32 v[68:69], v[68:69], v[76:77]
	s_waitcnt lgkmcnt(2)
	v_lshlrev_b32_e32 v87, 16, v86
	v_lshlrev_b32_e32 v86, 16, v81
	s_waitcnt lgkmcnt(0)
	v_lshlrev_b32_e32 v81, 16, v80
	v_lshlrev_b32_e32 v80, 16, v88
	v_pk_add_f32 v[66:67], v[66:67], v[82:83]
	v_pk_add_f32 v[68:69], v[68:69], v[84:85]
	v_pk_add_f32 v[66:67], v[66:67], v[86:87]
	v_pk_add_f32 v[68:69], v[68:69], v[80:81]
	s_nop 0
	v_pk_add_f32 v[66:67], v[66:67], v[68:69]
	s_nop 0
	v_add_f32_e32 v66, v66, v67
	v_lshl_add_u32 v67, v100, 2, 0
	v_add_u32_e32 v67, 0x18c00, v67
	ds_write_b32 v67, v66
	s_waitcnt lgkmcnt(0)
	s_barrier
	s_and_saveexec_b64 s[0:1], vcc
	s_xor_b64 s[0:1], exec, s[0:1]
	s_lshl_b32 s8, s61, 2
	s_xor_b32 s9, s21, 15
	s_or_saveexec_b64 s[0:1], s[0:1]
	v_mov_b32_e32 v66, s9
	v_mov_b32_e32 v67, s8
	s_xor_b64 exec, exec, s[0:1]
	s_cbranch_execz .LBB0_446
	v_and_b32_e32 v66, 0x7f, v100
	v_lshlrev_b32_e32 v67, 10, v79
	s_add_i32 s8, 0, 0x18c00
	v_lshlrev_b32_e32 v68, 2, v66
	v_add3_u32 v66, s8, v67, v68
	ds_read2st64_b32 v[70:71], v66 offset1:2
	s_lshl_b32 s8, s61, 2
	v_mov_b32_e32 v67, s8
	v_lshl_add_u32 v66, v79, 5, s8
	s_xor_b32 s8, s21, 15
	s_waitcnt lgkmcnt(0)
	v_add_f32_e32 v72, v70, v71
	v_or_b32_e32 v69, s31, v66
	v_mov_b32_e32 v66, s8
	v_mov_b32_e32 v70, s21
	v_cmp_gt_u32_e32 vcc, s96, v100
	s_nop 1
	v_cndmask_b32_e32 v70, v66, v70, vcc
	v_lshl_or_b32 v70, v69, 4, v70
	v_ashrrev_i32_e32 v71, 31, v70
	v_lshlrev_b64 v[70:71], 9, v[70:71]
	v_lshl_add_u64 v[70:71], s[38:39], 0, v[70:71]
	v_mov_b32_e32 v69, v179
	v_lshl_add_u64 v[68:69], v[70:71], 0, v[68:69]
	global_store_dword v[68:69], v72, off sc1
	s_branch .LBB0_446

.LBB0_623:
	s_or_b64 exec, exec, s[0:1]
	s_waitcnt lgkmcnt(0)
	ds_read_b128 v[66:69], v144 offset:128
	ds_read_b128 v[70:73], v144 offset:160
	s_lshl_b32 s0, s93, 16
	s_add_i32 s0, s0, 0
	s_lshl_b32 s1, s61, 14
	s_waitcnt lgkmcnt(1)
	v_mul_f32_e32 v74, v2, v66
	v_mul_f32_e32 v18, v18, v66
	v_mul_f32_e32 v34, v34, v66
	v_mul_f32_e32 v50, v50, v66
	v_mul_f32_e32 v66, v3, v67
	v_mul_f32_e32 v19, v19, v67
	v_mul_f32_e32 v35, v35, v67
	v_mul_f32_e32 v51, v51, v67
	v_mul_f32_e32 v67, v4, v68
	v_mul_f32_e32 v20, v20, v68
	v_mul_f32_e32 v36, v36, v68
	v_mul_f32_e32 v52, v52, v68
	v_mul_f32_e32 v68, v5, v69
	ds_read_b128 v[2:5], v144 offset:192
	s_add_i32 s0, s0, s1
	s_waitcnt lgkmcnt(1)
	v_mul_f32_e32 v6, v6, v70
	v_mul_f32_e32 v22, v22, v70
	v_mul_f32_e32 v7, v7, v71
	s_waitcnt lgkmcnt(0)
	v_mul_f32_e32 v10, v10, v2
	v_mul_f32_e32 v26, v26, v2
	v_mul_f32_e32 v42, v42, v2
	v_mul_f32_e32 v58, v58, v2
	v_mul_f32_e32 v11, v11, v3
	v_mul_f32_e32 v27, v27, v3
	v_mul_f32_e32 v43, v43, v3
	v_mul_f32_e32 v59, v59, v3
	v_mul_f32_e32 v12, v12, v4
	v_mul_f32_e32 v28, v28, v4
	v_mul_f32_e32 v44, v44, v4
	v_mul_f32_e32 v60, v60, v4
	v_mul_f32_e32 v13, v13, v5
	v_mul_f32_e32 v29, v29, v5
	v_mul_f32_e32 v45, v45, v5
	v_mul_f32_e32 v61, v61, v5
	ds_read_b128 v[2:5], v144 offset:224
	s_waitcnt lgkmcnt(0)
	s_barrier
	v_mul_f32_e32 v21, v21, v69
	v_mul_f32_e32 v14, v14, v2
	v_mul_f32_e32 v30, v30, v2
	v_mul_f32_e32 v46, v46, v2
	v_mul_f32_e32 v2, v62, v2
	v_mul_f32_e32 v15, v15, v3
	v_mul_f32_e32 v31, v31, v3
	v_mul_f32_e32 v47, v47, v3
	v_mul_f32_e32 v3, v63, v3
	v_lshlrev_b32_e32 v62, 11, v136
	v_lshlrev_b32_e32 v63, 2, v135
	v_add3_u32 v62, s0, v62, v63
	ds_write2_b32 v62, v74, v18 offset1:32
	ds_write2_b32 v62, v66, v19 offset0:128 offset1:160
	v_add_u32_e32 v18, 0x400, v62
	v_add_u32_e32 v19, 0x1000, v62
	v_mul_f32_e32 v23, v23, v71
	v_mul_f32_e32 v8, v8, v72
	v_mul_f32_e32 v24, v24, v72
	v_mul_f32_e32 v9, v9, v73
	ds_write2_b32 v18, v67, v20 offset1:32
	ds_write2_b32 v18, v68, v21 offset0:128 offset1:160
	ds_write2_b32 v19, v6, v22 offset1:32
	ds_write2_b32 v19, v7, v23 offset0:128 offset1:160
	v_add_u32_e32 v6, 0x1400, v62
	v_add_u32_e32 v7, 0x2000, v62
	v_mul_f32_e32 v25, v25, v73
	v_mul_f32_e32 v16, v16, v4
	v_mul_f32_e32 v32, v32, v4
	ds_write2_b32 v6, v8, v24 offset1:32
	ds_write2_b32 v6, v9, v25 offset0:128 offset1:160
	ds_write2_b32 v7, v10, v26 offset1:32
	ds_write2_b32 v7, v11, v27 offset0:128 offset1:160
	v_add_u32_e32 v8, 0x2400, v62
	v_add_u32_e32 v9, 0x3000, v62
	v_add_u32_e32 v10, 0x3400, v62
	v_mul_f32_e32 v37, v37, v69
	v_mul_f32_e32 v53, v53, v69
	v_mul_f32_e32 v38, v38, v70
	v_mul_f32_e32 v54, v54, v70
	v_mul_f32_e32 v39, v39, v71
	v_mul_f32_e32 v55, v55, v71
	v_mul_f32_e32 v40, v40, v72
	v_mul_f32_e32 v56, v56, v72
	v_mul_f32_e32 v41, v41, v73
	v_mul_f32_e32 v57, v57, v73
	v_mul_f32_e32 v48, v48, v4
	v_mul_f32_e32 v4, v64, v4
	v_mul_f32_e32 v17, v17, v5
	v_mul_f32_e32 v33, v33, v5
	v_mul_f32_e32 v49, v49, v5
	v_mul_f32_e32 v5, v65, v5
	ds_write2_b32 v8, v12, v28 offset1:32
	ds_write2_b32 v8, v13, v29 offset0:128 offset1:160
	ds_write2_b32 v9, v14, v30 offset1:32
	ds_write2_b32 v9, v15, v31 offset0:128 offset1:160
	ds_write2_b32 v10, v16, v32 offset1:32
	ds_write2_b32 v10, v17, v33 offset0:128 offset1:160
	ds_write2_b32 v62, v34, v50 offset0:64 offset1:96
	ds_write2_b32 v62, v35, v51 offset0:192 offset1:224
	ds_write2_b32 v18, v36, v52 offset0:64 offset1:96
	ds_write2_b32 v18, v37, v53 offset0:192 offset1:224
	ds_write2_b32 v19, v38, v54 offset0:64 offset1:96
	ds_write2_b32 v19, v39, v55 offset0:192 offset1:224
	ds_write2_b32 v6, v40, v56 offset0:64 offset1:96
	ds_write2_b32 v6, v41, v57 offset0:192 offset1:224
	ds_write2_b32 v7, v42, v58 offset0:64 offset1:96
	ds_write2_b32 v7, v43, v59 offset0:192 offset1:224
	ds_write2_b32 v8, v44, v60 offset0:64 offset1:96
	ds_write2_b32 v8, v45, v61 offset0:192 offset1:224
	ds_write2_b32 v9, v46, v2 offset0:64 offset1:96
	ds_write2_b32 v9, v47, v3 offset0:192 offset1:224
	ds_write2_b32 v10, v48, v4 offset0:64 offset1:96
	ds_write2_b32 v10, v49, v5 offset0:192 offset1:224
	v_add_u32_e32 v34, s60, v170
	v_mov_b64_e32 v[2:3], s[28:29]
	v_mad_i64_i32 v[4:5], s[0:1], v34, s36, v[2:3]
	v_lshl_add_u64 v[4:5], v[4:5], 0, s[82:83]
	v_lshl_add_u64 v[4:5], v[4:5], 0, v[178:179]
	global_load_dwordx4 v[14:17], v[4:5], off offset:3072
	v_add_u32_e32 v4, 0x200, v168
	v_ashrrev_i32_e32 v40, 4, v4
	v_add_u32_e32 v32, s60, v40
	v_mad_i64_i32 v[4:5], s[0:1], v32, s36, v[2:3]
	v_lshl_add_u64 v[4:5], v[4:5], 0, s[82:83]
	v_lshl_add_u64 v[4:5], v[4:5], 0, v[178:179]
	global_load_dwordx4 v[10:13], v[4:5], off offset:3072
	v_add_u32_e32 v4, 0x400, v168
	v_ashrrev_i32_e32 v39, 4, v4
	v_add_u32_e32 v30, s60, v39
	v_mad_i64_i32 v[4:5], s[0:1], v30, s36, v[2:3]
	v_lshl_add_u64 v[4:5], v[4:5], 0, s[82:83]
	v_lshl_add_u64 v[4:5], v[4:5], 0, v[178:179]
	global_load_dwordx4 v[6:9], v[4:5], off offset:3072
	v_add_u32_e32 v4, 0x600, v168
	v_ashrrev_i32_e32 v36, 4, v4
	v_add_u32_e32 v26, s60, v36
	v_mad_i64_i32 v[2:3], s[0:1], v26, s36, v[2:3]
	v_lshlrev_b32_e32 v18, 2, v169
	v_lshl_add_u64 v[2:3], v[2:3], 0, s[82:83]
	v_add_u32_e32 v38, 0, v18
	v_add_u32_e32 v37, s92, v18
	v_lshlrev_b32_e32 v22, 2, v134
	v_lshl_add_u64 v[2:3], v[2:3], 0, v[178:179]
	v_add_u32_e32 v18, v38, v22
	v_add_u32_e32 v22, v37, v22
	global_load_dwordx4 v[2:5], v[2:3], off offset:3072
	s_waitcnt lgkmcnt(0)
	s_barrier
	ds_read_b128 v[42:45], v18
	ds_read_b128 v[18:21], v18 offset:16
	ds_read_b128 v[46:49], v22
	ds_read_b128 v[22:25], v22 offset:16
	v_ashrrev_i32_e32 v35, 31, v34
	v_mov_b32_e32 v155, v179
	v_lshl_add_u64 v[28:29], s[22:23], 0, v[154:155]
	s_waitcnt lgkmcnt(1)
	v_pk_add_f32 v[42:43], v[42:43], v[46:47]
	v_pk_add_f32 v[44:45], v[44:45], v[48:49]
	s_waitcnt lgkmcnt(0)
	v_pk_add_f32 v[18:19], v[18:19], v[22:23]
	v_pk_add_f32 v[20:21], v[20:21], v[24:25]
	v_ashrrev_i32_e32 v33, 31, v32
	v_ashrrev_i32_e32 v31, 31, v30
	v_ashrrev_i32_e32 v27, 31, v26
	s_add_i32 s31, s31, s3
	s_cmpk_lt_i32 s31, 0x200
	s_waitcnt vmcnt(3)
	v_lshlrev_b32_e32 v41, 16, v14
	v_and_b32_e32 v14, 0xffff0000, v14
	v_mul_f32_e32 v41, 0xbfb8aa3b, v41
	v_mul_f32_e32 v14, 0xbfb8aa3b, v14
	v_exp_f32_e32 v50, v41
	v_exp_f32_e32 v51, v14
	s_nop 0
	v_pk_add_f32 v[50:51], v[50:51], 1.0 op_sel_hi:[1,0]
	s_nop 0
	v_rcp_f32_e32 v41, v51
	s_nop 0
	s_nop 0
	v_mul_f32_e32 v53, 1.0, v41
	v_fma_f32 v54, -v51, v53, 1.0
	v_fma_f32 v14, v54, v41, v53
	v_div_fixup_f32 v51, v14, v51, 1.0
	v_rcp_f32_e32 v41, v50
	s_nop 0
	s_nop 0
	v_mul_f32_e32 v53, 1.0, v41
	v_fma_f32 v54, -v50, v53, 1.0
	v_fma_f32 v14, v54, v41, v53
	v_div_fixup_f32 v50, v14, v50, 1.0
	v_lshlrev_b32_e32 v41, 16, v15
	v_and_b32_e32 v15, 0xffff0000, v15
	v_pk_mul_f32 v[42:43], v[50:51], v[42:43]
	v_mul_f32_e32 v41, 0xbfb8aa3b, v41
	v_mul_f32_e32 v15, 0xbfb8aa3b, v15
	v_cvt_pk_bf16_f32 v14, v42, v43
	v_exp_f32_e32 v42, v41
	v_exp_f32_e32 v43, v15
	s_nop 0
	v_pk_add_f32 v[42:43], v[42:43], 1.0 op_sel_hi:[1,0]
	s_nop 0
	v_rcp_f32_e32 v41, v43
	s_nop 0
	s_nop 0
	v_mul_f32_e32 v47, 1.0, v41
	v_fma_f32 v48, -v43, v47, 1.0
	v_fma_f32 v15, v48, v41, v47
	v_div_fixup_f32 v43, v15, v43, 1.0
	v_rcp_f32_e32 v41, v42
	s_nop 0
	s_nop 0
	v_mul_f32_e32 v47, 1.0, v41
	v_fma_f32 v48, -v42, v47, 1.0
	v_fma_f32 v15, v48, v41, v47
	v_div_fixup_f32 v42, v15, v42, 1.0
	v_lshlrev_b32_e32 v41, 16, v16
	v_and_b32_e32 v16, 0xffff0000, v16
	v_pk_mul_f32 v[42:43], v[42:43], v[44:45]
	v_mul_f32_e32 v41, 0xbfb8aa3b, v41
	v_mul_f32_e32 v16, 0xbfb8aa3b, v16
	v_cvt_pk_bf16_f32 v15, v42, v43
	v_exp_f32_e32 v42, v41
	v_exp_f32_e32 v43, v16
	s_nop 0
	v_pk_add_f32 v[42:43], v[42:43], 1.0 op_sel_hi:[1,0]
	s_nop 0
	v_rcp_f32_e32 v41, v43
	s_nop 0
	s_nop 0
	v_mul_f32_e32 v45, 1.0, v41
	v_fma_f32 v46, -v43, v45, 1.0
	v_fma_f32 v16, v46, v41, v45
	v_div_fixup_f32 v43, v16, v43, 1.0
	v_rcp_f32_e32 v41, v42
	s_nop 0
	s_nop 0
	v_mul_f32_e32 v45, 1.0, v41
	v_fma_f32 v46, -v42, v45, 1.0
	v_fma_f32 v16, v46, v41, v45
	v_div_fixup_f32 v42, v16, v42, 1.0
	v_pk_mul_f32 v[18:19], v[42:43], v[18:19]
	s_nop 0
	v_cvt_pk_bf16_f32 v16, v18, v19
	v_lshlrev_b32_e32 v18, 16, v17
	v_and_b32_e32 v17, 0xffff0000, v17
	v_mul_f32_e32 v18, 0xbfb8aa3b, v18
	v_mul_f32_e32 v17, 0xbfb8aa3b, v17
	v_exp_f32_e32 v18, v18
	v_exp_f32_e32 v19, v17
	s_nop 0
	v_pk_add_f32 v[18:19], v[18:19], 1.0 op_sel_hi:[1,0]
	s_nop 0
	v_rcp_f32_e32 v22, v19
	s_nop 0
	s_nop 0
	v_mul_f32_e32 v24, 1.0, v22
	v_fma_f32 v25, -v19, v24, 1.0
	v_fma_f32 v17, v25, v22, v24
	v_div_fixup_f32 v19, v17, v19, 1.0
	v_rcp_f32_e32 v22, v18
	s_nop 0
	s_nop 0
	v_mul_f32_e32 v24, 1.0, v22
	v_fma_f32 v25, -v18, v24, 1.0
	v_fma_f32 v17, v25, v22, v24
	v_div_fixup_f32 v18, v17, v18, 1.0
	v_pk_mul_f32 v[18:19], v[18:19], v[20:21]
	s_nop 0
	v_cvt_pk_bf16_f32 v17, v18, v19
	v_lshlrev_b64 v[18:19], 11, v[34:35]
	s_waitcnt vmcnt(2)
	v_lshlrev_b32_e32 v34, 16, v10
	v_and_b32_e32 v10, 0xffff0000, v10
	v_mul_f32_e32 v34, 0xbfb8aa3b, v34
	v_mul_f32_e32 v10, 0xbfb8aa3b, v10
	v_exp_f32_e32 v34, v34
	v_exp_f32_e32 v35, v10
	v_lshl_add_u64 v[18:19], v[28:29], 0, v[18:19]
	global_store_dwordx4 v[18:19], v[14:17], off sc1
	v_lshlrev_b32_e32 v18, 9, v40
	v_pk_add_f32 v[34:35], v[34:35], 1.0 op_sel_hi:[1,0]
	v_add_u32_e32 v14, v38, v18
	v_rcp_f32_e32 v44, v35
	v_add_u32_e32 v18, v37, v18
	ds_read_b128 v[22:25], v14
	ds_read_b128 v[14:17], v14 offset:16
	ds_read_b128 v[40:43], v18
	ds_read_b128 v[18:21], v18 offset:16
	s_nop 0
	v_mul_f32_e32 v46, 1.0, v44
	v_fma_f32 v47, -v35, v46, 1.0
	v_fma_f32 v10, v47, v44, v46
	v_div_fixup_f32 v35, v10, v35, 1.0
	v_rcp_f32_e32 v44, v34
	s_waitcnt lgkmcnt(1)
	v_pk_add_f32 v[22:23], v[22:23], v[40:41]
	v_pk_add_f32 v[24:25], v[24:25], v[42:43]
	s_waitcnt lgkmcnt(0)
	v_pk_add_f32 v[14:15], v[14:15], v[18:19]
	s_nop 0
	v_mul_f32_e32 v46, 1.0, v44
	v_fma_f32 v47, -v34, v46, 1.0
	v_fma_f32 v10, v47, v44, v46
	v_div_fixup_f32 v34, v10, v34, 1.0
	v_pk_mul_f32 v[22:23], v[34:35], v[22:23]
	v_pk_add_f32 v[16:17], v[16:17], v[20:21]
	v_cvt_pk_bf16_f32 v10, v22, v23
	v_lshlrev_b32_e32 v22, 16, v11
	v_and_b32_e32 v11, 0xffff0000, v11
	v_mul_f32_e32 v22, 0xbfb8aa3b, v22
	v_mul_f32_e32 v11, 0xbfb8aa3b, v11
	v_exp_f32_e32 v22, v22
	v_exp_f32_e32 v23, v11
	s_nop 0
	v_pk_add_f32 v[22:23], v[22:23], 1.0 op_sel_hi:[1,0]
	s_nop 0
	v_rcp_f32_e32 v34, v23
	s_nop 0
	s_nop 0
	v_mul_f32_e32 v40, 1.0, v34
	v_fma_f32 v41, -v23, v40, 1.0
	v_fma_f32 v11, v41, v34, v40
	v_div_fixup_f32 v23, v11, v23, 1.0
	v_rcp_f32_e32 v34, v22
	s_nop 0
	s_nop 0
	v_mul_f32_e32 v40, 1.0, v34
	v_fma_f32 v41, -v22, v40, 1.0
	v_fma_f32 v11, v41, v34, v40
	v_div_fixup_f32 v22, v11, v22, 1.0
	v_pk_mul_f32 v[22:23], v[22:23], v[24:25]
	s_nop 0
	v_cvt_pk_bf16_f32 v11, v22, v23
	v_lshlrev_b32_e32 v22, 16, v12
	v_and_b32_e32 v12, 0xffff0000, v12
	v_mul_f32_e32 v22, 0xbfb8aa3b, v22
	v_mul_f32_e32 v12, 0xbfb8aa3b, v12
	v_exp_f32_e32 v22, v22
	v_exp_f32_e32 v23, v12
	s_nop 0
	v_pk_add_f32 v[22:23], v[22:23], 1.0 op_sel_hi:[1,0]
	s_nop 0
	v_rcp_f32_e32 v24, v23
	s_nop 0
	s_nop 0
	v_mul_f32_e32 v34, 1.0, v24
	v_fma_f32 v35, -v23, v34, 1.0
	v_fma_f32 v12, v35, v24, v34
	v_div_fixup_f32 v23, v12, v23, 1.0
	v_rcp_f32_e32 v24, v22
	s_nop 0
	s_nop 0
	v_mul_f32_e32 v34, 1.0, v24
	v_fma_f32 v35, -v22, v34, 1.0
	v_fma_f32 v12, v35, v24, v34
	v_div_fixup_f32 v22, v12, v22, 1.0
	v_pk_mul_f32 v[14:15], v[22:23], v[14:15]
	s_nop 0
	v_cvt_pk_bf16_f32 v12, v14, v15
	v_lshlrev_b32_e32 v14, 16, v13
	v_and_b32_e32 v13, 0xffff0000, v13
	v_mul_f32_e32 v14, 0xbfb8aa3b, v14
	v_mul_f32_e32 v13, 0xbfb8aa3b, v13
	v_exp_f32_e32 v14, v14
	v_exp_f32_e32 v15, v13
	s_nop 0
	v_pk_add_f32 v[14:15], v[14:15], 1.0 op_sel_hi:[1,0]
	s_nop 0
	v_rcp_f32_e32 v18, v15
	s_nop 0
	s_nop 0
	v_mul_f32_e32 v20, 1.0, v18
	v_fma_f32 v21, -v15, v20, 1.0
	v_fma_f32 v13, v21, v18, v20
	v_div_fixup_f32 v15, v13, v15, 1.0
	v_rcp_f32_e32 v18, v14
	s_nop 0
	s_nop 0
	v_mul_f32_e32 v20, 1.0, v18
	v_fma_f32 v21, -v14, v20, 1.0
	v_fma_f32 v13, v21, v18, v20
	v_div_fixup_f32 v14, v13, v14, 1.0
	v_pk_mul_f32 v[14:15], v[14:15], v[16:17]
	s_nop 0
	v_cvt_pk_bf16_f32 v13, v14, v15
	v_lshlrev_b64 v[14:15], 11, v[32:33]
	s_waitcnt vmcnt(2)
	v_lshlrev_b32_e32 v32, 16, v6
	v_and_b32_e32 v6, 0xffff0000, v6
	v_mul_f32_e32 v32, 0xbfb8aa3b, v32
	v_mul_f32_e32 v6, 0xbfb8aa3b, v6
	v_exp_f32_e32 v32, v32
	v_exp_f32_e32 v33, v6
	v_lshl_add_u64 v[14:15], v[28:29], 0, v[14:15]
	global_store_dwordx4 v[14:15], v[10:13], off sc1
	v_lshlrev_b32_e32 v14, 9, v39
	v_pk_add_f32 v[32:33], v[32:33], 1.0 op_sel_hi:[1,0]
	v_add_u32_e32 v10, v38, v14
	v_rcp_f32_e32 v34, v33
	v_add_u32_e32 v14, v37, v14
	ds_read_b128 v[18:21], v10
	ds_read_b128 v[10:13], v10 offset:16
	ds_read_b128 v[22:25], v14
	ds_read_b128 v[14:17], v14 offset:16
	s_nop 0
	v_mul_f32_e32 v39, 1.0, v34
	v_fma_f32 v40, -v33, v39, 1.0
	v_fma_f32 v6, v40, v34, v39
	v_div_fixup_f32 v33, v6, v33, 1.0
	v_rcp_f32_e32 v34, v32
	s_waitcnt lgkmcnt(1)
	v_pk_add_f32 v[18:19], v[18:19], v[22:23]
	v_pk_add_f32 v[20:21], v[20:21], v[24:25]
	s_waitcnt lgkmcnt(0)
	v_pk_add_f32 v[10:11], v[10:11], v[14:15]
	s_nop 0
	v_mul_f32_e32 v39, 1.0, v34
	v_fma_f32 v40, -v32, v39, 1.0
	v_fma_f32 v6, v40, v34, v39
	v_div_fixup_f32 v32, v6, v32, 1.0
	v_pk_mul_f32 v[18:19], v[32:33], v[18:19]
	v_pk_add_f32 v[12:13], v[12:13], v[16:17]
	v_cvt_pk_bf16_f32 v6, v18, v19
	v_lshlrev_b32_e32 v18, 16, v7
	v_and_b32_e32 v7, 0xffff0000, v7
	v_mul_f32_e32 v18, 0xbfb8aa3b, v18
	v_mul_f32_e32 v7, 0xbfb8aa3b, v7
	v_exp_f32_e32 v18, v18
	v_exp_f32_e32 v19, v7
	s_nop 0
	v_pk_add_f32 v[18:19], v[18:19], 1.0 op_sel_hi:[1,0]
	s_nop 0
	v_rcp_f32_e32 v22, v19
	s_nop 0
	s_nop 0
	v_mul_f32_e32 v24, 1.0, v22
	v_fma_f32 v25, -v19, v24, 1.0
	v_fma_f32 v7, v25, v22, v24
	v_div_fixup_f32 v19, v7, v19, 1.0
	v_rcp_f32_e32 v22, v18
	s_nop 0
	s_nop 0
	v_mul_f32_e32 v24, 1.0, v22
	v_fma_f32 v25, -v18, v24, 1.0
	v_fma_f32 v7, v25, v22, v24
	v_div_fixup_f32 v18, v7, v18, 1.0
	v_pk_mul_f32 v[18:19], v[18:19], v[20:21]
	s_nop 0
	v_cvt_pk_bf16_f32 v7, v18, v19
	v_lshlrev_b32_e32 v18, 16, v8
	v_and_b32_e32 v8, 0xffff0000, v8
	v_mul_f32_e32 v18, 0xbfb8aa3b, v18
	v_mul_f32_e32 v8, 0xbfb8aa3b, v8
	v_exp_f32_e32 v18, v18
	v_exp_f32_e32 v19, v8
	s_nop 0
	v_pk_add_f32 v[18:19], v[18:19], 1.0 op_sel_hi:[1,0]
	s_nop 0
	v_rcp_f32_e32 v20, v19
	s_nop 0
	s_nop 0
	v_mul_f32_e32 v22, 1.0, v20
	v_fma_f32 v23, -v19, v22, 1.0
	v_fma_f32 v8, v23, v20, v22
	v_div_fixup_f32 v19, v8, v19, 1.0
	v_rcp_f32_e32 v20, v18
	s_nop 0
	s_nop 0
	v_mul_f32_e32 v22, 1.0, v20
	v_fma_f32 v23, -v18, v22, 1.0
	v_fma_f32 v8, v23, v20, v22
	v_div_fixup_f32 v18, v8, v18, 1.0
	v_pk_mul_f32 v[10:11], v[18:19], v[10:11]
	s_waitcnt vmcnt(2)
	v_lshlrev_b32_e32 v22, 16, v2
	v_cvt_pk_bf16_f32 v8, v10, v11
	v_lshlrev_b32_e32 v10, 16, v9
	v_and_b32_e32 v9, 0xffff0000, v9
	v_mul_f32_e32 v10, 0xbfb8aa3b, v10
	v_mul_f32_e32 v9, 0xbfb8aa3b, v9
	v_exp_f32_e32 v10, v10
	v_exp_f32_e32 v11, v9
	v_and_b32_e32 v2, 0xffff0000, v2
	v_mul_f32_e32 v22, 0xbfb8aa3b, v22
	v_mul_f32_e32 v2, 0xbfb8aa3b, v2
	v_pk_add_f32 v[10:11], v[10:11], 1.0 op_sel_hi:[1,0]
	v_exp_f32_e32 v22, v22
	v_rcp_f32_e32 v14, v11
	v_exp_f32_e32 v23, v2
	s_nop 0
	v_mul_f32_e32 v16, 1.0, v14
	v_fma_f32 v17, -v11, v16, 1.0
	v_fma_f32 v9, v17, v14, v16
	v_div_fixup_f32 v11, v9, v11, 1.0
	v_rcp_f32_e32 v14, v10
	v_pk_add_f32 v[22:23], v[22:23], 1.0 op_sel_hi:[1,0]
	s_nop 0
	v_mul_f32_e32 v16, 1.0, v14
	v_fma_f32 v17, -v10, v16, 1.0
	v_rcp_f32_e32 v24, v23
	v_fma_f32 v9, v17, v14, v16
	v_div_fixup_f32 v10, v9, v10, 1.0
	s_nop 0
	v_pk_mul_f32 v[10:11], v[10:11], v[12:13]
	v_cvt_pk_bf16_f32 v9, v10, v11
	v_lshlrev_b64 v[10:11], 11, v[30:31]
	v_mul_f32_e32 v30, 1.0, v24
	v_fma_f32 v31, -v23, v30, 1.0
	v_fma_f32 v2, v31, v24, v30
	v_div_fixup_f32 v23, v2, v23, 1.0
	v_rcp_f32_e32 v24, v22
	v_lshl_add_u64 v[10:11], v[28:29], 0, v[10:11]
	global_store_dwordx4 v[10:11], v[6:9], off sc1
	v_lshlrev_b32_e32 v10, 9, v36
	s_nop 0
	v_add_u32_e32 v6, v38, v10
	v_add_u32_e32 v10, v37, v10
	v_mul_f32_e32 v30, 1.0, v24
	ds_read_b128 v[14:17], v6
	ds_read_b128 v[6:9], v6 offset:16
	ds_read_b128 v[18:21], v10
	ds_read_b128 v[10:13], v10 offset:16
	v_fma_f32 v31, -v22, v30, 1.0
	v_fma_f32 v2, v31, v24, v30
	v_div_fixup_f32 v22, v2, v22, 1.0
	s_waitcnt lgkmcnt(1)
	v_pk_add_f32 v[14:15], v[14:15], v[18:19]
	v_pk_add_f32 v[16:17], v[16:17], v[20:21]
	v_pk_mul_f32 v[14:15], v[22:23], v[14:15]
	s_waitcnt lgkmcnt(0)
	v_pk_add_f32 v[6:7], v[6:7], v[10:11]
	v_cvt_pk_bf16_f32 v2, v14, v15
	v_lshlrev_b32_e32 v14, 16, v3
	v_and_b32_e32 v3, 0xffff0000, v3
	v_mul_f32_e32 v14, 0xbfb8aa3b, v14
	v_mul_f32_e32 v3, 0xbfb8aa3b, v3
	v_exp_f32_e32 v14, v14
	v_exp_f32_e32 v15, v3
	v_pk_add_f32 v[8:9], v[8:9], v[12:13]
	v_pk_add_f32 v[14:15], v[14:15], 1.0 op_sel_hi:[1,0]
	s_nop 0
	v_rcp_f32_e32 v18, v15
	s_nop 0
	s_nop 0
	v_mul_f32_e32 v20, 1.0, v18
	v_fma_f32 v21, -v15, v20, 1.0
	v_fma_f32 v3, v21, v18, v20
	v_div_fixup_f32 v15, v3, v15, 1.0
	v_rcp_f32_e32 v18, v14
	s_nop 0
	s_nop 0
	v_mul_f32_e32 v20, 1.0, v18
	v_fma_f32 v21, -v14, v20, 1.0
	v_fma_f32 v3, v21, v18, v20
	v_div_fixup_f32 v14, v3, v14, 1.0
	v_pk_mul_f32 v[14:15], v[14:15], v[16:17]
	s_nop 0
	v_cvt_pk_bf16_f32 v3, v14, v15
	v_lshlrev_b32_e32 v14, 16, v4
	v_and_b32_e32 v4, 0xffff0000, v4
	v_mul_f32_e32 v14, 0xbfb8aa3b, v14
	v_mul_f32_e32 v4, 0xbfb8aa3b, v4
	v_exp_f32_e32 v14, v14
	v_exp_f32_e32 v15, v4
	s_nop 0
	v_pk_add_f32 v[14:15], v[14:15], 1.0 op_sel_hi:[1,0]
	s_nop 0
	v_rcp_f32_e32 v16, v15
	s_nop 0
	s_nop 0
	v_mul_f32_e32 v18, 1.0, v16
	v_fma_f32 v19, -v15, v18, 1.0
	v_fma_f32 v4, v19, v16, v18
	v_div_fixup_f32 v15, v4, v15, 1.0
	v_rcp_f32_e32 v16, v14
	s_nop 0
	s_nop 0
	v_mul_f32_e32 v18, 1.0, v16
	v_fma_f32 v19, -v14, v18, 1.0
	v_fma_f32 v4, v19, v16, v18
	v_div_fixup_f32 v14, v4, v14, 1.0
	v_pk_mul_f32 v[6:7], v[14:15], v[6:7]
	s_nop 0
	v_cvt_pk_bf16_f32 v4, v6, v7
	v_lshlrev_b32_e32 v6, 16, v5
	v_and_b32_e32 v5, 0xffff0000, v5
	v_mul_f32_e32 v6, 0xbfb8aa3b, v6
	v_mul_f32_e32 v5, 0xbfb8aa3b, v5
	v_exp_f32_e32 v6, v6
	v_exp_f32_e32 v7, v5
	s_nop 0
	v_pk_add_f32 v[6:7], v[6:7], 1.0 op_sel_hi:[1,0]
	s_nop 0
	v_rcp_f32_e32 v10, v7
	s_nop 0
	s_nop 0
	v_mul_f32_e32 v12, 1.0, v10
	v_fma_f32 v13, -v7, v12, 1.0
	v_fma_f32 v5, v13, v10, v12
	v_div_fixup_f32 v7, v5, v7, 1.0
	v_rcp_f32_e32 v10, v6
	s_nop 0
	s_nop 0
	v_mul_f32_e32 v12, 1.0, v10
	v_fma_f32 v13, -v6, v12, 1.0
	v_fma_f32 v5, v13, v10, v12
	v_div_fixup_f32 v6, v5, v6, 1.0
	v_pk_mul_f32 v[6:7], v[6:7], v[8:9]
	s_nop 0
	v_cvt_pk_bf16_f32 v5, v6, v7
	v_lshlrev_b64 v[6:7], 11, v[26:27]
	v_lshl_add_u64 v[6:7], v[28:29], 0, v[6:7]
	global_store_dwordx4 v[6:7], v[2:5], off sc1
	s_barrier
	s_cbranch_scc0 .LBB0_690

.LBB0_658:
	s_or_b64 exec, exec, s[0:1]
	s_lshl_b32 s0, s93, 11
	s_add_i32 s94, s0, 0
	s_lshl_b32 s0, s93, 5
	s_add_i32 s0, s0, s40
	s_or_b32 s0, s0, s38
	s_add_i32 s94, s94, 0x20000
	s_lshl_b32 s4, s0, 4
	s_and_b64 s[0:1], s[14:15], exec
	s_cselect_b32 s0, s33, s39
	v_add_u32_e32 v48, s60, v176
	v_mov_b64_e32 v[46:47], s[28:29]
	s_or_b32 s38, s4, s0
	v_mad_i64_i32 v[34:35], s[0:1], v48, s36, v[46:47]
	v_or_b32_e32 v38, 1, v48
	v_or_b32_e32 v42, 2, v48
	v_or_b32_e32 v48, 3, v48
	v_mad_i64_i32 v[38:39], s[0:1], v38, s36, v[46:47]
	v_mad_i64_i32 v[42:43], s[0:1], v42, s36, v[46:47]
	v_mad_i64_i32 v[46:47], s[0:1], v48, s36, v[46:47]
	v_lshlrev_b32_e32 v164, 2, v114
	v_mov_b32_e32 v165, v179
	v_lshl_add_u64 v[156:157], s[34:35], 0, v[164:165]
	s_mov_b64 s[0:1], 0x1000
	v_lshl_add_u64 v[118:119], v[156:157], 0, s[0:1]
	s_movk_i32 s0, 0x1000
	v_add_co_u32_e32 v166, vcc, s0, v156
	s_movk_i32 s0, 0x2000
	s_nop 0
	v_addc_co_u32_e32 v167, vcc, 0, v157, vcc
	s_lshl_b32 s82, s41, 1
	v_add_co_u32_e32 v158, vcc, s0, v156
	s_mov_b64 s[0:1], 0x2000
	v_lshl_add_u64 v[34:35], v[34:35], 0, s[82:83]
	v_lshl_add_u64 v[38:39], v[38:39], 0, s[82:83]
	v_lshl_add_u64 v[42:43], v[42:43], 0, s[82:83]
	v_lshl_add_u64 v[46:47], v[46:47], 0, s[82:83]
	v_lshl_add_u64 v[122:123], v[156:157], 0, s[0:1]
	s_mov_b64 s[0:1], 0x3000
	v_lshl_add_u64 v[34:35], v[34:35], 0, v[178:179]
	v_lshl_add_u64 v[38:39], v[38:39], 0, v[178:179]
	v_lshl_add_u64 v[42:43], v[42:43], 0, v[178:179]
	v_lshl_add_u64 v[46:47], v[46:47], 0, v[178:179]
	v_addc_co_u32_e32 v159, vcc, 0, v157, vcc
	v_lshl_add_u64 v[126:127], v[156:157], 0, s[0:1]
	s_movk_i32 s0, 0x3000
	global_load_dwordx4 v[34:37], v[34:35], off offset:2048
	v_add_co_u32_e32 v162, vcc, s0, v156
	global_load_dwordx4 v[38:41], v[38:39], off offset:2048
	s_nop 0
	v_addc_co_u32_e32 v163, vcc, 0, v157, vcc
	global_load_dwordx4 v[42:45], v[42:43], off offset:2048
	s_movk_i32 s0, 0x4000
	global_load_dwordx4 v[46:49], v[46:47], off offset:2048
	s_nop 0
	global_load_dwordx4 v[114:117], v164, s[34:35] offset:16
	global_load_dwordx4 v[134:137], v164, s[34:35]
	global_load_dwordx4 v[138:141], v[158:159], off offset:-4096
	s_nop 0
	global_load_dwordx4 v[118:121], v[118:119], off offset:16
	v_add_co_u32_e32 v160, vcc, s0, v156
	global_load_dwordx4 v[142:145], v[158:159], off
	s_nop 0
	global_load_dwordx4 v[122:125], v[122:123], off offset:16
	v_addc_co_u32_e32 v161, vcc, 0, v157, vcc
	s_mov_b64 s[0:1], 0x4000
	global_load_dwordx4 v[146:149], v[160:161], off offset:-4096
	s_nop 0
	global_load_dwordx4 v[126:129], v[126:127], off offset:16
	v_lshl_add_u64 v[130:131], v[156:157], 0, s[0:1]
	global_load_dwordx4 v[150:153], v[160:161], off
	s_nop 0
	global_load_dwordx4 v[130:133], v[130:131], off offset:16
	s_waitcnt vmcnt(14)
	v_lshlrev_b32_e32 v224, 16, v82
	v_and_b32_e32 v225, 0xffff0000, v82
	v_lshlrev_b32_e32 v220, 16, v86
	v_and_b32_e32 v221, 0xffff0000, v86
	v_lshlrev_b32_e32 v216, 16, v90
	v_and_b32_e32 v217, 0xffff0000, v90
	v_lshlrev_b32_e32 v196, 16, v102
	v_and_b32_e32 v197, 0xffff0000, v102
	v_lshlrev_b32_e32 v198, 16, v98
	v_and_b32_e32 v199, 0xffff0000, v98
	v_lshlrev_b32_e32 v214, 16, v106
	v_and_b32_e32 v215, 0xffff0000, v106
	v_lshlrev_b32_e32 v212, 16, v110
	v_and_b32_e32 v213, 0xffff0000, v110
	s_add_i32 s92, 0, 0x10000
	s_waitcnt vmcnt(8)
	v_pk_fma_f32 v[224:225], v[134:135], v[224:225], 0 op_sel_hi:[1,1,0]
	v_pk_fma_f32 v[222:223], v[134:135], v[220:221], 0 op_sel_hi:[1,1,0]
	s_waitcnt vmcnt(7)
	v_pk_fma_f32 v[220:221], v[138:139], v[220:221], v[224:225]
	v_pk_fma_f32 v[218:219], v[134:135], v[216:217], 0 op_sel_hi:[1,1,0]
	v_pk_fma_f32 v[222:223], v[138:139], v[216:217], v[222:223]
	s_waitcnt vmcnt(5)
	v_pk_fma_f32 v[216:217], v[142:143], v[216:217], v[220:221]
	v_pk_fma_f32 v[134:135], v[134:135], v[196:197], 0 op_sel_hi:[1,1,0]
	s_waitcnt vmcnt(3)
	v_pk_fma_f32 v[216:217], v[146:147], v[196:197], v[216:217]
	v_pk_fma_f32 v[134:135], v[138:139], v[198:199], v[134:135]
	s_waitcnt vmcnt(1)
	v_pk_fma_f32 v[216:217], v[150:151], v[198:199], v[216:217]
	v_pk_fma_f32 v[134:135], v[142:143], v[212:213], v[134:135]
	v_mul_f32_e32 v82, 0xbfb8aa3b, v216
	v_exp_f32_e32 v220, v82
	v_mul_f32_e32 v82, 0xbfb8aa3b, v217
	v_exp_f32_e32 v221, v82
	v_pk_fma_f32 v[134:135], v[146:147], v[214:215], v[134:135]
	v_pk_add_f32 v[220:221], v[220:221], 1.0 op_sel_hi:[1,0]
	s_nop 0
	v_rcp_f32_e32 v86, v221
	s_nop 0
	s_nop 0
	v_mul_f32_e32 v98, v217, v86
	v_fma_f32 v102, -v221, v98, v217
	v_fma_f32 v82, v102, v86, v98
	v_rcp_f32_e32 v90, v220
	v_div_fixup_f32 v82, v82, v221, v217
	s_nop 0
	v_mul_f32_e32 v102, v216, v90
	v_fma_f32 v106, -v220, v102, v216
	v_fma_f32 v86, v106, v90, v102
	v_div_fixup_f32 v86, v86, v220, v216
	v_pk_fma_f32 v[216:217], v[142:143], v[196:197], v[222:223]
	v_cvt_pk_bf16_f32 v82, v86, v82
	v_pk_fma_f32 v[216:217], v[146:147], v[198:199], v[216:217]
	s_nop 0
	v_pk_fma_f32 v[216:217], v[150:151], v[212:213], v[216:217]
	s_nop 0
	v_mul_f32_e32 v86, 0xbfb8aa3b, v216
	v_exp_f32_e32 v220, v86
	v_mul_f32_e32 v86, 0xbfb8aa3b, v217
	v_exp_f32_e32 v221, v86
	s_nop 0
	v_pk_add_f32 v[220:221], v[220:221], 1.0 op_sel_hi:[1,0]
	s_nop 0
	v_rcp_f32_e32 v90, v221
	s_nop 0
	s_nop 0
	v_mul_f32_e32 v102, v217, v90
	v_fma_f32 v106, -v221, v102, v217
	v_fma_f32 v86, v106, v90, v102
	v_rcp_f32_e32 v98, v220
	v_div_fixup_f32 v86, v86, v221, v217
	s_nop 0
	v_mul_f32_e32 v106, v216, v98
	v_fma_f32 v110, -v220, v106, v216
	v_fma_f32 v90, v110, v98, v106
	v_div_fixup_f32 v90, v90, v220, v216
	v_pk_fma_f32 v[216:217], v[138:139], v[196:197], v[218:219]
	v_cvt_pk_bf16_f32 v86, v90, v86
	v_pk_fma_f32 v[216:217], v[142:143], v[198:199], v[216:217]
	v_lshlrev_b32_e32 v138, 16, v94
	v_pk_fma_f32 v[216:217], v[146:147], v[212:213], v[216:217]
	v_and_b32_e32 v139, 0xffff0000, v94
	v_pk_fma_f32 v[216:217], v[150:151], v[214:215], v[216:217]
	v_pk_fma_f32 v[134:135], v[150:151], v[138:139], v[134:135]
	v_mul_f32_e32 v90, 0xbfb8aa3b, v216
	v_exp_f32_e32 v218, v90
	v_mul_f32_e32 v90, 0xbfb8aa3b, v217
	v_exp_f32_e32 v219, v90
	v_mul_f32_e32 v94, 0xbfb8aa3b, v134
	v_exp_f32_e32 v138, v94
	v_mul_f32_e32 v94, 0xbfb8aa3b, v135
	v_pk_add_f32 v[218:219], v[218:219], 1.0 op_sel_hi:[1,0]
	v_exp_f32_e32 v139, v94
	v_rcp_f32_e32 v98, v219
	v_pk_add_f32 v[138:139], v[138:139], 1.0 op_sel_hi:[1,0]
	v_lshlrev_b32_e32 v150, 16, v83
	s_nop 0
	v_mul_f32_e32 v106, v217, v98
	v_fma_f32 v110, -v219, v106, v217
	v_fma_f32 v90, v110, v98, v106
	v_rcp_f32_e32 v102, v218
	v_div_fixup_f32 v90, v90, v219, v217
	v_and_b32_e32 v151, 0xffff0000, v83
	v_lshlrev_b32_e32 v142, 16, v87
	s_nop 0
	v_mul_f32_e32 v110, v216, v102
	v_fma_f32 v155, -v218, v110, v216
	v_fma_f32 v98, v155, v102, v110
	v_div_fixup_f32 v98, v98, v218, v216
	v_cvt_pk_bf16_f32 v90, v98, v90
	v_rcp_f32_e32 v98, v139
	v_and_b32_e32 v143, 0xffff0000, v87
	v_pk_fma_f32 v[150:151], v[136:137], v[150:151], 0 op_sel_hi:[1,1,0]
	v_pk_fma_f32 v[146:147], v[136:137], v[142:143], 0 op_sel_hi:[1,1,0]
	s_nop 0
	v_mul_f32_e32 v106, v135, v98
	v_fma_f32 v110, -v139, v106, v135
	v_fma_f32 v94, v110, v98, v106
	v_div_fixup_f32 v155, v94, v139, v135
	v_rcp_f32_e32 v98, v138
	v_and_b32_e32 v135, 0xffff0000, v91
	v_pk_fma_f32 v[142:143], v[140:141], v[142:143], v[150:151]
	s_nop 0
	v_mul_f32_e32 v106, v134, v98
	v_fma_f32 v110, -v138, v106, v134
	v_fma_f32 v94, v110, v98, v106
	v_div_fixup_f32 v165, v94, v138, v134
	v_lshlrev_b32_e32 v134, 16, v91
	v_lshlrev_b32_e32 v102, 16, v103
	v_and_b32_e32 v103, 0xffff0000, v103
	v_pk_fma_f32 v[138:139], v[136:137], v[134:135], 0 op_sel_hi:[1,1,0]
	v_pk_fma_f32 v[146:147], v[140:141], v[134:135], v[146:147]
	v_pk_fma_f32 v[134:135], v[144:145], v[134:135], v[142:143]
	v_lshlrev_b32_e32 v98, 16, v99
	v_and_b32_e32 v99, 0xffff0000, v99
	v_pk_fma_f32 v[134:135], v[148:149], v[102:103], v[134:135]
	v_lshlrev_b32_e32 v110, 16, v111
	v_pk_fma_f32 v[134:135], v[152:153], v[98:99], v[134:135]
	v_and_b32_e32 v111, 0xffff0000, v111
	v_mul_f32_e32 v83, 0xbfb8aa3b, v134
	v_exp_f32_e32 v142, v83
	v_mul_f32_e32 v83, 0xbfb8aa3b, v135
	v_exp_f32_e32 v143, v83
	v_lshlrev_b32_e32 v106, 16, v107
	v_and_b32_e32 v107, 0xffff0000, v107
	v_pk_add_f32 v[142:143], v[142:143], 1.0 op_sel_hi:[1,0]
	s_nop 0
	v_rcp_f32_e32 v87, v143
	s_nop 0
	s_nop 0
	v_mul_f32_e32 v94, v135, v87
	v_fma_f32 v150, -v143, v94, v135
	v_fma_f32 v83, v150, v87, v94
	v_rcp_f32_e32 v91, v142
	v_div_fixup_f32 v83, v83, v143, v135
	s_nop 0
	v_mul_f32_e32 v135, v134, v91
	v_fma_f32 v143, -v142, v135, v134
	v_fma_f32 v87, v143, v91, v135
	v_div_fixup_f32 v87, v87, v142, v134
	v_pk_fma_f32 v[134:135], v[144:145], v[102:103], v[146:147]
	v_cvt_pk_bf16_f32 v83, v87, v83
	v_pk_fma_f32 v[134:135], v[148:149], v[98:99], v[134:135]
	s_nop 0
	v_pk_fma_f32 v[134:135], v[152:153], v[110:111], v[134:135]
	s_nop 0
	v_mul_f32_e32 v87, 0xbfb8aa3b, v134
	v_exp_f32_e32 v142, v87
	v_mul_f32_e32 v87, 0xbfb8aa3b, v135
	v_exp_f32_e32 v143, v87
	s_nop 0
	v_pk_add_f32 v[142:143], v[142:143], 1.0 op_sel_hi:[1,0]
	s_nop 0
	v_rcp_f32_e32 v91, v143
	s_nop 0
	s_nop 0
	v_mul_f32_e32 v146, v135, v91
	v_fma_f32 v147, -v143, v146, v135
	v_fma_f32 v87, v147, v91, v146
	v_rcp_f32_e32 v94, v142
	v_div_fixup_f32 v87, v87, v143, v135
	s_nop 0
	v_mul_f32_e32 v143, v134, v94
	v_fma_f32 v146, -v142, v143, v134
	v_fma_f32 v91, v146, v94, v143
	v_div_fixup_f32 v91, v91, v142, v134
	v_pk_fma_f32 v[134:135], v[140:141], v[102:103], v[138:139]
	v_cvt_pk_bf16_f32 v87, v91, v87
	v_pk_fma_f32 v[134:135], v[144:145], v[98:99], v[134:135]
	v_pk_fma_f32 v[102:103], v[136:137], v[102:103], 0 op_sel_hi:[1,1,0]
	v_pk_fma_f32 v[134:135], v[148:149], v[110:111], v[134:135]
	v_pk_fma_f32 v[98:99], v[140:141], v[98:99], v[102:103]
	v_pk_fma_f32 v[134:135], v[152:153], v[106:107], v[134:135]
	v_pk_fma_f32 v[98:99], v[144:145], v[110:111], v[98:99]
	v_mul_f32_e32 v91, 0xbfb8aa3b, v134
	v_exp_f32_e32 v138, v91
	v_mul_f32_e32 v91, 0xbfb8aa3b, v135
	v_exp_f32_e32 v139, v91
	v_pk_fma_f32 v[98:99], v[148:149], v[106:107], v[98:99]
	v_lshlrev_b32_e32 v140, 16, v84
	v_and_b32_e32 v141, 0xffff0000, v84
	v_pk_add_f32 v[138:139], v[138:139], 1.0 op_sel_hi:[1,0]
	v_lshlrev_b32_e32 v136, 16, v88
	v_rcp_f32_e32 v94, v139
	v_and_b32_e32 v137, 0xffff0000, v88
	v_pk_fma_f32 v[140:141], v[114:115], v[140:141], 0 op_sel_hi:[1,1,0]
	v_and_b32_e32 v111, 0xffff0000, v92
	s_nop 0
	v_mul_f32_e32 v143, v135, v94
	v_fma_f32 v146, -v139, v143, v135
	v_fma_f32 v91, v146, v94, v143
	v_div_fixup_f32 v91, v91, v139, v135
	v_rcp_f32_e32 v135, v138
	v_lshlrev_b32_e32 v144, 16, v54
	v_and_b32_e32 v145, 0xffff0000, v54
	s_nop 0
	v_mul_f32_e32 v142, v134, v135
	v_fma_f32 v143, -v138, v142, v134
	v_fma_f32 v94, v143, v135, v142
	v_div_fixup_f32 v94, v94, v138, v134
	v_cvt_pk_bf16_f32 v91, v94, v91
	v_lshlrev_b32_e32 v94, 16, v95
	v_and_b32_e32 v95, 0xffff0000, v95
	v_pk_fma_f32 v[94:95], v[152:153], v[94:95], v[98:99]
	v_pk_fma_f32 v[138:139], v[114:115], v[136:137], 0 op_sel_hi:[1,1,0]
	v_mul_f32_e32 v98, 0xbfb8aa3b, v94
	v_mul_f32_e32 v99, 0xbfb8aa3b, v95
	v_exp_f32_e32 v98, v98
	v_exp_f32_e32 v99, v99
	v_pk_fma_f32 v[136:137], v[118:119], v[136:137], v[140:141]
	v_lshlrev_b32_e32 v140, 16, v58
	v_and_b32_e32 v141, 0xffff0000, v58
	v_pk_add_f32 v[98:99], v[98:99], 1.0 op_sel_hi:[1,0]
	s_nop 0
	v_rcp_f32_e32 v103, v99
	s_nop 0
	s_nop 0
	v_mul_f32_e32 v107, v95, v103
	v_fma_f32 v110, -v99, v107, v95
	v_fma_f32 v102, v110, v103, v107
	v_div_fixup_f32 v142, v102, v99, v95
	v_rcp_f32_e32 v99, v98
	v_lshlrev_b32_e32 v110, 16, v92
	v_pk_fma_f32 v[134:135], v[114:115], v[110:111], 0 op_sel_hi:[1,1,0]
	v_pk_fma_f32 v[138:139], v[118:119], v[110:111], v[138:139]
	s_nop 0
	v_mul_f32_e32 v103, v94, v99
	v_fma_f32 v106, -v98, v103, v94
	v_fma_f32 v95, v106, v99, v103
	v_div_fixup_f32 v143, v95, v98, v94
	v_lshlrev_b32_e32 v94, 16, v104
	v_and_b32_e32 v95, 0xffff0000, v104
	v_pk_fma_f32 v[110:111], v[122:123], v[110:111], v[136:137]
	v_lshlrev_b32_e32 v98, 16, v100
	v_and_b32_e32 v99, 0xffff0000, v100
	v_pk_fma_f32 v[110:111], v[126:127], v[94:95], v[110:111]
	v_lshlrev_b32_e32 v106, 16, v108
	s_waitcnt vmcnt(0)
	v_pk_fma_f32 v[110:111], v[130:131], v[98:99], v[110:111]
	v_and_b32_e32 v107, 0xffff0000, v108
	v_mul_f32_e32 v84, 0xbfb8aa3b, v110
	v_exp_f32_e32 v136, v84
	v_mul_f32_e32 v84, 0xbfb8aa3b, v111
	v_exp_f32_e32 v137, v84
	v_lshlrev_b32_e32 v102, 16, v112
	v_and_b32_e32 v103, 0xffff0000, v112
	v_pk_add_f32 v[136:137], v[136:137], 1.0 op_sel_hi:[1,0]
	s_nop 0
	v_rcp_f32_e32 v88, v137
	s_nop 0
	s_nop 0
	v_mul_f32_e32 v100, v111, v88
	v_fma_f32 v104, -v137, v100, v111
	v_fma_f32 v84, v104, v88, v100
	v_rcp_f32_e32 v92, v136
	v_div_fixup_f32 v84, v84, v137, v111
	s_nop 0
	v_mul_f32_e32 v104, v110, v92
	v_fma_f32 v108, -v136, v104, v110
	v_fma_f32 v88, v108, v92, v104
	v_div_fixup_f32 v88, v88, v136, v110
	v_pk_fma_f32 v[110:111], v[122:123], v[94:95], v[138:139]
	v_cvt_pk_bf16_f32 v84, v88, v84
	v_pk_fma_f32 v[110:111], v[126:127], v[98:99], v[110:111]
	v_lshlrev_b32_e32 v138, 16, v62
	v_pk_fma_f32 v[110:111], v[130:131], v[102:103], v[110:111]
	v_and_b32_e32 v139, 0xffff0000, v62
	v_mul_f32_e32 v88, 0xbfb8aa3b, v110
	v_exp_f32_e32 v136, v88
	v_mul_f32_e32 v88, 0xbfb8aa3b, v111
	v_exp_f32_e32 v137, v88
	s_nop 0
	v_pk_add_f32 v[136:137], v[136:137], 1.0 op_sel_hi:[1,0]
	s_nop 0
	v_rcp_f32_e32 v92, v137
	s_nop 0
	s_nop 0
	v_mul_f32_e32 v104, v111, v92
	v_fma_f32 v108, -v137, v104, v111
	v_fma_f32 v88, v108, v92, v104
	v_rcp_f32_e32 v100, v136
	v_div_fixup_f32 v88, v88, v137, v111
	s_nop 0
	v_mul_f32_e32 v108, v110, v100
	v_fma_f32 v111, -v136, v108, v110
	v_fma_f32 v92, v111, v100, v108
	v_div_fixup_f32 v92, v92, v136, v110
	v_pk_fma_f32 v[110:111], v[118:119], v[94:95], v[134:135]
	v_cvt_pk_bf16_f32 v88, v92, v88
	v_pk_fma_f32 v[110:111], v[122:123], v[98:99], v[110:111]
	v_pk_fma_f32 v[94:95], v[114:115], v[94:95], 0 op_sel_hi:[1,1,0]
	v_pk_fma_f32 v[110:111], v[126:127], v[102:103], v[110:111]
	v_pk_fma_f32 v[94:95], v[118:119], v[98:99], v[94:95]
	v_pk_fma_f32 v[110:111], v[130:131], v[106:107], v[110:111]
	v_pk_fma_f32 v[94:95], v[122:123], v[102:103], v[94:95]
	v_mul_f32_e32 v92, 0xbfb8aa3b, v110
	v_exp_f32_e32 v134, v92
	v_mul_f32_e32 v92, 0xbfb8aa3b, v111
	v_exp_f32_e32 v135, v92
	v_pk_fma_f32 v[94:95], v[126:127], v[106:107], v[94:95]
	v_lshlrev_b32_e32 v98, 16, v96
	v_and_b32_e32 v99, 0xffff0000, v96
	v_pk_add_f32 v[134:135], v[134:135], 1.0 op_sel_hi:[1,0]
	v_pk_fma_f32 v[94:95], v[130:131], v[98:99], v[94:95]
	v_rcp_f32_e32 v100, v135
	v_mul_f32_e32 v96, 0xbfb8aa3b, v94
	v_exp_f32_e32 v98, v96
	v_mul_f32_e32 v96, 0xbfb8aa3b, v95
	s_nop 0
	v_mul_f32_e32 v108, v111, v100
	v_fma_f32 v112, -v135, v108, v111
	v_fma_f32 v92, v112, v100, v108
	v_rcp_f32_e32 v104, v134
	v_div_fixup_f32 v92, v92, v135, v111
	v_exp_f32_e32 v99, v96
	v_lshlrev_b32_e32 v122, 16, v70
	s_nop 0
	v_mul_f32_e32 v111, v110, v104
	v_fma_f32 v112, -v134, v111, v110
	v_fma_f32 v100, v112, v104, v111
	v_pk_add_f32 v[98:99], v[98:99], 1.0 op_sel_hi:[1,0]
	v_div_fixup_f32 v100, v100, v134, v110
	v_cvt_pk_bf16_f32 v92, v100, v92
	v_rcp_f32_e32 v100, v99
	v_lshlrev_b32_e32 v112, 16, v85
	v_lshlrev_b32_e32 v108, 16, v89
	v_and_b32_e32 v123, 0xffff0000, v70
	s_nop 0
	v_mul_f32_e32 v103, v95, v100
	v_fma_f32 v104, -v99, v103, v95
	v_fma_f32 v96, v104, v100, v103
	v_div_fixup_f32 v114, v96, v99, v95
	v_rcp_f32_e32 v96, v98
	v_and_b32_e32 v103, 0xffff0000, v109
	v_lshlrev_b32_e32 v104, 16, v93
	v_lshlrev_b32_e32 v126, 16, v78
	s_nop 0
	v_mul_f32_e32 v100, v94, v96
	v_fma_f32 v102, -v98, v100, v94
	v_fma_f32 v95, v102, v96, v100
	v_div_fixup_f32 v115, v95, v98, v94
	v_lshlrev_b32_e32 v98, 16, v101
	v_and_b32_e32 v99, 0xffff0000, v101
	v_lshlrev_b32_e32 v100, 16, v113
	v_and_b32_e32 v101, 0xffff0000, v113
	v_and_b32_e32 v113, 0xffff0000, v85
	v_lshlrev_b32_e32 v102, 16, v109
	v_and_b32_e32 v109, 0xffff0000, v89
	v_pk_fma_f32 v[112:113], v[116:117], v[112:113], 0 op_sel_hi:[1,1,0]
	v_lshlrev_b32_e32 v94, 16, v105
	v_and_b32_e32 v95, 0xffff0000, v105
	v_and_b32_e32 v105, 0xffff0000, v93
	v_pk_fma_f32 v[110:111], v[116:117], v[108:109], 0 op_sel_hi:[1,1,0]
	v_pk_fma_f32 v[108:109], v[120:121], v[108:109], v[112:113]
	v_pk_fma_f32 v[106:107], v[116:117], v[104:105], 0 op_sel_hi:[1,1,0]
	v_pk_fma_f32 v[110:111], v[120:121], v[104:105], v[110:111]
	v_pk_fma_f32 v[104:105], v[124:125], v[104:105], v[108:109]
	v_and_b32_e32 v127, 0xffff0000, v78
	v_pk_fma_f32 v[104:105], v[128:129], v[94:95], v[104:105]
	v_lshlrev_b32_e32 v134, 7, v170
	v_pk_fma_f32 v[104:105], v[132:133], v[98:99], v[104:105]
	s_nop 0
	v_mul_f32_e32 v85, 0xbfb8aa3b, v104
	v_exp_f32_e32 v108, v85
	v_mul_f32_e32 v85, 0xbfb8aa3b, v105
	v_exp_f32_e32 v109, v85
	s_nop 0
	v_pk_add_f32 v[108:109], v[108:109], 1.0 op_sel_hi:[1,0]
	s_nop 0
	v_rcp_f32_e32 v89, v109
	s_nop 0
	s_nop 0
	v_mul_f32_e32 v96, v105, v89
	v_fma_f32 v112, -v109, v96, v105
	v_fma_f32 v85, v112, v89, v96
	v_rcp_f32_e32 v93, v108
	v_div_fixup_f32 v85, v85, v109, v105
	s_nop 0
	v_mul_f32_e32 v105, v104, v93
	v_fma_f32 v109, -v108, v105, v104
	v_fma_f32 v89, v109, v93, v105
	v_div_fixup_f32 v89, v89, v108, v104
	v_pk_fma_f32 v[104:105], v[124:125], v[94:95], v[110:111]
	v_cvt_pk_bf16_f32 v85, v89, v85
	v_pk_fma_f32 v[104:105], v[128:129], v[98:99], v[104:105]
	s_nop 0
	v_pk_fma_f32 v[104:105], v[132:133], v[100:101], v[104:105]
	s_nop 0
	v_mul_f32_e32 v89, 0xbfb8aa3b, v104
	v_exp_f32_e32 v108, v89
	v_mul_f32_e32 v89, 0xbfb8aa3b, v105
	v_exp_f32_e32 v109, v89
	s_nop 0
	v_pk_add_f32 v[108:109], v[108:109], 1.0 op_sel_hi:[1,0]
	s_nop 0
	v_rcp_f32_e32 v93, v109
	s_nop 0
	s_nop 0
	v_mul_f32_e32 v110, v105, v93
	v_fma_f32 v111, -v109, v110, v105
	v_fma_f32 v89, v111, v93, v110
	v_rcp_f32_e32 v96, v108
	v_div_fixup_f32 v89, v89, v109, v105
	s_nop 0
	v_mul_f32_e32 v109, v104, v96
	v_fma_f32 v110, -v108, v109, v104
	v_fma_f32 v93, v110, v96, v109
	v_div_fixup_f32 v93, v93, v108, v104
	v_pk_fma_f32 v[104:105], v[120:121], v[94:95], v[106:107]
	v_cvt_pk_bf16_f32 v89, v93, v89
	v_pk_fma_f32 v[104:105], v[124:125], v[98:99], v[104:105]
	v_pk_fma_f32 v[94:95], v[116:117], v[94:95], 0 op_sel_hi:[1,1,0]
	v_pk_fma_f32 v[104:105], v[128:129], v[100:101], v[104:105]
	v_pk_fma_f32 v[94:95], v[120:121], v[98:99], v[94:95]
	v_pk_fma_f32 v[104:105], v[132:133], v[102:103], v[104:105]
	v_pk_fma_f32 v[94:95], v[124:125], v[100:101], v[94:95]
	v_mul_f32_e32 v93, 0xbfb8aa3b, v104
	v_exp_f32_e32 v106, v93
	v_mul_f32_e32 v93, 0xbfb8aa3b, v105
	v_exp_f32_e32 v107, v93
	v_pk_fma_f32 v[94:95], v[128:129], v[102:103], v[94:95]
	v_lshlrev_b32_e32 v124, 16, v66
	v_and_b32_e32 v125, 0xffff0000, v66
	v_pk_add_f32 v[106:107], v[106:107], 1.0 op_sel_hi:[1,0]
	v_lshlrev_b32_e32 v128, 16, v74
	v_rcp_f32_e32 v96, v107
	v_and_b32_e32 v129, 0xffff0000, v74
	s_nop 0
	v_mul_f32_e32 v109, v105, v96
	v_fma_f32 v110, -v107, v109, v105
	v_fma_f32 v93, v110, v96, v109
	v_div_fixup_f32 v93, v93, v107, v105
	v_rcp_f32_e32 v105, v106
	s_nop 0
	s_nop 0
	v_mul_f32_e32 v108, v104, v105
	v_fma_f32 v109, -v106, v108, v104
	v_fma_f32 v96, v109, v105, v108
	v_div_fixup_f32 v96, v96, v106, v104
	v_cvt_pk_bf16_f32 v93, v96, v93
	v_lshlrev_b32_e32 v96, 16, v97
	v_and_b32_e32 v97, 0xffff0000, v97
	v_pk_fma_f32 v[94:95], v[132:133], v[96:97], v[94:95]
	s_nop 0
	v_mul_f32_e32 v96, 0xbfb8aa3b, v94
	v_mul_f32_e32 v97, 0xbfb8aa3b, v95
	v_exp_f32_e32 v96, v96
	v_exp_f32_e32 v97, v97
	s_nop 0
	v_pk_add_f32 v[96:97], v[96:97], 1.0 op_sel_hi:[1,0]
	s_nop 0
	v_rcp_f32_e32 v99, v97
	s_nop 0
	s_nop 0
	v_mul_f32_e32 v101, v95, v99
	v_fma_f32 v102, -v97, v101, v95
	v_fma_f32 v98, v102, v99, v101
	v_div_fixup_f32 v97, v98, v97, v95
	v_rcp_f32_e32 v98, v96
	s_movk_i32 s0, 0xc0
	s_nop 0
	v_mul_f32_e32 v100, v94, v98
	v_fma_f32 v101, -v96, v100, v94
	v_fma_f32 v95, v101, v98, v100
	v_div_fixup_f32 v98, v95, v96, v94
	v_lshlrev_b32_e32 v99, 6, v170
	v_cvt_pk_bf16_f32 v97, v98, v97
	v_lshlrev_b32_e32 v98, 10, v170
	v_bitop3_b32 v99, v99, v178, s0 bitop3:0x6c
	v_add3_u32 v132, 0, v98, v99
	ds_write_b128 v132, v[82:85]
	v_or_b32_e32 v82, 1, v176
	v_lshlrev_b32_e32 v83, 8, v82
	v_lshlrev_b32_e32 v82, 4, v82
	s_movk_i32 s0, 0xd0
	v_bitop3_b32 v82, v82, v178, s0 bitop3:0x6c
	v_add3_u32 v133, 0, v83, v82
	v_or_b32_e32 v82, 2, v176
	v_lshlrev_b32_e32 v83, 8, v82
	v_lshlrev_b32_e32 v82, 4, v82
	s_movk_i32 s0, 0xe0
	v_bitop3_b32 v82, v82, v178, s0 bitop3:0x6c
	v_add3_u32 v135, 0, v83, v82
	v_or_b32_e32 v82, 3, v176
	v_lshlrev_b32_e32 v83, 8, v82
	v_lshlrev_b32_e32 v82, 4, v82
	s_movk_i32 s0, 0xf0
	v_bitop3_b32 v82, v82, v178, s0 bitop3:0x6c
	v_cvt_pk_bf16_f32 v94, v165, v155
	v_cvt_pk_bf16_f32 v95, v143, v142
	v_cvt_pk_bf16_f32 v96, v115, v114
	v_add3_u32 v136, 0, v83, v82
	ds_write_b128 v133, v[86:89]
	ds_write_b128 v135, v[90:93]
	ds_write_b128 v136, v[94:97]
	global_load_dwordx4 v[82:85], v164, s[34:35] offset:2064
	global_load_dwordx4 v[90:93], v164, s[34:35] offset:2048
	s_mov_b64 s[0:1], 0x1800
	v_lshl_add_u64 v[86:87], v[156:157], 0, s[0:1]
	s_mov_b64 s[0:1], 0x2800
	global_load_dwordx4 v[94:97], v[166:167], off offset:2048
	s_nop 0
	global_load_dwordx4 v[86:89], v[86:87], off offset:16
	v_lshl_add_u64 v[98:99], v[156:157], 0, s[0:1]
	s_mov_b64 s[0:1], 0x3800
	global_load_dwordx4 v[106:109], v[158:159], off offset:2048
	s_nop 0
	global_load_dwordx4 v[98:101], v[98:99], off offset:16
	v_lshl_add_u64 v[102:103], v[156:157], 0, s[0:1]
	s_mov_b64 s[0:1], 0x4800
	global_load_dwordx4 v[110:113], v[162:163], off offset:2048
	s_nop 0
	global_load_dwordx4 v[102:105], v[102:103], off offset:16
	v_lshl_add_u64 v[118:119], v[156:157], 0, s[0:1]
	global_load_dwordx4 v[114:117], v[160:161], off offset:2048
	s_nop 0
	global_load_dwordx4 v[118:121], v[118:119], off offset:16
	s_waitcnt vmcnt(8)
	v_pk_fma_f32 v[144:145], v[90:91], v[144:145], 0 op_sel_hi:[1,1,0]
	v_pk_fma_f32 v[142:143], v[90:91], v[140:141], 0 op_sel_hi:[1,1,0]
	v_pk_fma_f32 v[130:131], v[90:91], v[138:139], 0 op_sel_hi:[1,1,0]
	s_waitcnt vmcnt(7)
	v_pk_fma_f32 v[140:141], v[94:95], v[140:141], v[144:145]
	v_pk_fma_f32 v[142:143], v[94:95], v[138:139], v[142:143]
	v_pk_fma_f32 v[130:131], v[94:95], v[122:123], v[130:131]
	s_waitcnt vmcnt(5)
	v_pk_fma_f32 v[138:139], v[106:107], v[138:139], v[140:141]
	v_pk_fma_f32 v[130:131], v[106:107], v[124:125], v[130:131]
	v_pk_fma_f32 v[90:91], v[90:91], v[122:123], 0 op_sel_hi:[1,1,0]
	s_waitcnt vmcnt(3)
	v_pk_fma_f32 v[138:139], v[110:111], v[122:123], v[138:139]
	v_pk_fma_f32 v[130:131], v[110:111], v[126:127], v[130:131]
	s_waitcnt vmcnt(1)
	v_pk_fma_f32 v[138:139], v[114:115], v[124:125], v[138:139]
	v_pk_fma_f32 v[130:131], v[114:115], v[128:129], v[130:131]
	v_mul_f32_e32 v54, 0xbfb8aa3b, v138
	v_exp_f32_e32 v140, v54
	v_mul_f32_e32 v54, 0xbfb8aa3b, v139
	v_exp_f32_e32 v141, v54
	v_pk_fma_f32 v[90:91], v[94:95], v[124:125], v[90:91]
	v_lshlrev_b32_e32 v94, 16, v50
	v_pk_fma_f32 v[90:91], v[106:107], v[126:127], v[90:91]
	v_pk_add_f32 v[140:141], v[140:141], 1.0 op_sel_hi:[1,0]
	v_pk_fma_f32 v[90:91], v[110:111], v[128:129], v[90:91]
	v_rcp_f32_e32 v58, v141
	v_and_b32_e32 v95, 0xffff0000, v50
	v_pk_fma_f32 v[90:91], v[114:115], v[94:95], v[90:91]
	s_nop 0
	v_mul_f32_e32 v66, v139, v58
	v_fma_f32 v70, -v141, v66, v139
	v_fma_f32 v54, v70, v58, v66
	v_div_fixup_f32 v139, v54, v141, v139
	v_rcp_f32_e32 v58, v140
	v_mul_f32_e32 v50, 0xbfb8aa3b, v90
	v_exp_f32_e32 v94, v50
	v_mul_f32_e32 v50, 0xbfb8aa3b, v91
	s_nop 0
	v_mul_f32_e32 v66, v138, v58
	v_fma_f32 v70, -v140, v66, v138
	v_fma_f32 v54, v70, v58, v66
	v_div_fixup_f32 v138, v54, v140, v138
	v_pk_mul_f32 v[138:139], v[138:139], s[26:27] op_sel_hi:[1,0]
	v_exp_f32_e32 v95, v50
	v_cvt_pk_bf16_f32 v54, v138, v139
	v_pk_fma_f32 v[138:139], v[106:107], v[122:123], v[142:143]
	v_lshlrev_b32_e32 v122, 16, v55
	v_pk_fma_f32 v[138:139], v[110:111], v[124:125], v[138:139]
	v_pk_add_f32 v[94:95], v[94:95], 1.0 op_sel_hi:[1,0]
	v_pk_fma_f32 v[138:139], v[114:115], v[126:127], v[138:139]
	v_mul_f32_e32 v58, 0xbfb8aa3b, v138
	v_exp_f32_e32 v140, v58
	v_mul_f32_e32 v58, 0xbfb8aa3b, v139
	v_exp_f32_e32 v141, v58
	v_and_b32_e32 v123, 0xffff0000, v55
	v_lshlrev_b32_e32 v110, 16, v59
	v_and_b32_e32 v111, 0xffff0000, v59
	v_pk_add_f32 v[140:141], v[140:141], 1.0 op_sel_hi:[1,0]
	v_pk_fma_f32 v[122:123], v[92:93], v[122:123], 0 op_sel_hi:[1,1,0]
	v_rcp_f32_e32 v62, v141
	v_lshlrev_b32_e32 v106, 16, v63
	v_and_b32_e32 v107, 0xffff0000, v63
	v_pk_fma_f32 v[114:115], v[92:93], v[110:111], 0 op_sel_hi:[1,1,0]
	s_nop 0
	v_mul_f32_e32 v70, v139, v62
	v_fma_f32 v74, -v141, v70, v139
	v_fma_f32 v58, v74, v62, v70
	v_div_fixup_f32 v139, v58, v141, v139
	v_rcp_f32_e32 v62, v140
	v_pk_fma_f32 v[110:111], v[96:97], v[110:111], v[122:123]
	v_pk_fma_f32 v[114:115], v[96:97], v[106:107], v[114:115]
	s_nop 0
	v_mul_f32_e32 v70, v138, v62
	v_fma_f32 v74, -v140, v70, v138
	v_fma_f32 v58, v74, v62, v70
	v_div_fixup_f32 v138, v58, v140, v138
	v_pk_mul_f32 v[138:139], v[138:139], s[26:27] op_sel_hi:[1,0]
	v_mul_f32_e32 v62, 0xbfb8aa3b, v130
	v_cvt_pk_bf16_f32 v58, v138, v139
	v_exp_f32_e32 v138, v62
	v_mul_f32_e32 v62, 0xbfb8aa3b, v131
	v_exp_f32_e32 v139, v62
	s_nop 0
	v_pk_add_f32 v[138:139], v[138:139], 1.0 op_sel_hi:[1,0]
	s_nop 0
	v_rcp_f32_e32 v66, v139
	s_nop 0
	s_nop 0
	v_mul_f32_e32 v74, v131, v66
	v_fma_f32 v78, -v139, v74, v131
	v_fma_f32 v62, v78, v66, v74
	v_div_fixup_f32 v131, v62, v139, v131
	v_rcp_f32_e32 v66, v138
	s_nop 0
	s_nop 0
	v_mul_f32_e32 v74, v130, v66
	v_fma_f32 v78, -v138, v74, v130
	v_fma_f32 v62, v78, v66, v74
	v_rcp_f32_e32 v66, v95
	v_div_fixup_f32 v130, v62, v138, v130
	v_pk_mul_f32 v[130:131], v[130:131], s[26:27] op_sel_hi:[1,0]
	s_nop 0
	v_mul_f32_e32 v74, v91, v66
	v_fma_f32 v78, -v95, v74, v91
	v_fma_f32 v50, v78, v66, v74
	v_div_fixup_f32 v91, v50, v95, v91
	v_rcp_f32_e32 v66, v94
	v_cvt_pk_bf16_f32 v62, v130, v131
	s_nop 0
	v_mul_f32_e32 v74, v90, v66
	v_fma_f32 v78, -v94, v74, v90
	v_fma_f32 v50, v78, v66, v74
	v_div_fixup_f32 v90, v50, v94, v90
	v_lshlrev_b32_e32 v70, 16, v71
	v_and_b32_e32 v71, 0xffff0000, v71
	v_pk_fma_f32 v[94:95], v[92:93], v[106:107], 0 op_sel_hi:[1,1,0]
	v_pk_fma_f32 v[106:107], v[108:109], v[106:107], v[110:111]
	v_lshlrev_b32_e32 v66, 16, v67
	v_and_b32_e32 v67, 0xffff0000, v67
	v_pk_fma_f32 v[106:107], v[112:113], v[70:71], v[106:107]
	v_lshlrev_b32_e32 v78, 16, v79
	v_pk_fma_f32 v[106:107], v[116:117], v[66:67], v[106:107]
	v_and_b32_e32 v79, 0xffff0000, v79
	v_mul_f32_e32 v50, 0xbfb8aa3b, v106
	v_exp_f32_e32 v110, v50
	v_mul_f32_e32 v50, 0xbfb8aa3b, v107
	v_exp_f32_e32 v111, v50
	v_pk_fma_f32 v[94:95], v[96:97], v[70:71], v[94:95]
	v_lshlrev_b32_e32 v74, 16, v75
	v_pk_fma_f32 v[94:95], v[108:109], v[66:67], v[94:95]
	v_pk_add_f32 v[110:111], v[110:111], 1.0 op_sel_hi:[1,0]
	v_and_b32_e32 v75, 0xffff0000, v75
	v_rcp_f32_e32 v55, v111
	v_pk_fma_f32 v[94:95], v[112:113], v[78:79], v[94:95]
	v_pk_mul_f32 v[90:91], v[90:91], s[26:27] op_sel_hi:[1,0]
	v_pk_fma_f32 v[94:95], v[116:117], v[74:75], v[94:95]
	s_nop 0
	v_mul_f32_e32 v63, v107, v55
	v_fma_f32 v122, -v111, v63, v107
	v_fma_f32 v50, v122, v55, v63
	v_div_fixup_f32 v107, v50, v111, v107
	v_rcp_f32_e32 v55, v110
	s_nop 0
	s_nop 0
	v_mul_f32_e32 v63, v106, v55
	v_fma_f32 v111, -v110, v63, v106
	v_fma_f32 v50, v111, v55, v63
	v_div_fixup_f32 v106, v50, v110, v106
	v_pk_mul_f32 v[106:107], v[106:107], s[26:27] op_sel_hi:[1,0]
	s_nop 0
	v_cvt_pk_bf16_f32 v55, v106, v107
	v_pk_fma_f32 v[106:107], v[108:109], v[70:71], v[114:115]
	v_pk_fma_f32 v[70:71], v[92:93], v[70:71], 0 op_sel_hi:[1,1,0]
	v_pk_fma_f32 v[106:107], v[112:113], v[66:67], v[106:107]
	v_pk_fma_f32 v[66:67], v[96:97], v[66:67], v[70:71]
	v_pk_fma_f32 v[106:107], v[116:117], v[78:79], v[106:107]
	v_pk_fma_f32 v[66:67], v[108:109], v[78:79], v[66:67]
	v_mul_f32_e32 v50, 0xbfb8aa3b, v106
	v_exp_f32_e32 v110, v50
	v_mul_f32_e32 v50, 0xbfb8aa3b, v107
	v_exp_f32_e32 v111, v50
	v_pk_fma_f32 v[66:67], v[112:113], v[74:75], v[66:67]
	v_lshlrev_b32_e32 v108, 16, v56
	v_and_b32_e32 v109, 0xffff0000, v56
	v_pk_add_f32 v[110:111], v[110:111], 1.0 op_sel_hi:[1,0]
	v_lshlrev_b32_e32 v96, 16, v60
	v_rcp_f32_e32 v59, v111
	v_and_b32_e32 v97, 0xffff0000, v60
	v_pk_fma_f32 v[108:109], v[82:83], v[108:109], 0 op_sel_hi:[1,1,0]
	v_and_b32_e32 v79, 0xffff0000, v76
	s_nop 0
	v_mul_f32_e32 v114, v107, v59
	v_fma_f32 v115, -v111, v114, v107
	v_fma_f32 v50, v115, v59, v114
	v_div_fixup_f32 v107, v50, v111, v107
	v_rcp_f32_e32 v59, v110
	s_nop 0
	s_nop 0
	v_mul_f32_e32 v111, v106, v59
	v_fma_f32 v114, -v110, v111, v106
	v_fma_f32 v50, v114, v59, v111
	v_div_fixup_f32 v106, v50, v110, v106
	v_pk_mul_f32 v[106:107], v[106:107], s[26:27] op_sel_hi:[1,0]
	v_mul_f32_e32 v50, 0xbfb8aa3b, v94
	v_cvt_pk_bf16_f32 v59, v106, v107
	v_exp_f32_e32 v106, v50
	v_mul_f32_e32 v50, 0xbfb8aa3b, v95
	v_exp_f32_e32 v107, v50
	s_nop 0
	v_pk_add_f32 v[106:107], v[106:107], 1.0 op_sel_hi:[1,0]
	s_nop 0
	v_rcp_f32_e32 v63, v107
	s_nop 0
	s_nop 0
	v_mul_f32_e32 v111, v95, v63
	v_fma_f32 v114, -v107, v111, v95
	v_fma_f32 v50, v114, v63, v111
	v_div_fixup_f32 v95, v50, v107, v95
	v_rcp_f32_e32 v63, v106
	s_nop 0
	s_nop 0
	v_mul_f32_e32 v110, v94, v63
	v_fma_f32 v111, -v106, v110, v94
	v_fma_f32 v50, v111, v63, v110
	v_div_fixup_f32 v94, v50, v106, v94
	v_lshlrev_b32_e32 v50, 16, v51
	v_and_b32_e32 v51, 0xffff0000, v51
	v_pk_fma_f32 v[50:51], v[116:117], v[50:51], v[66:67]
	v_pk_mul_f32 v[94:95], v[94:95], s[26:27] op_sel_hi:[1,0]
	v_mul_f32_e32 v66, 0xbfb8aa3b, v50
	v_mul_f32_e32 v67, 0xbfb8aa3b, v51
	v_exp_f32_e32 v66, v66
	v_exp_f32_e32 v67, v67
	v_cvt_pk_bf16_f32 v63, v94, v95
	v_lshlrev_b32_e32 v94, 16, v64
	v_and_b32_e32 v95, 0xffff0000, v64
	v_pk_add_f32 v[66:67], v[66:67], 1.0 op_sel_hi:[1,0]
	v_pk_fma_f32 v[106:107], v[82:83], v[96:97], 0 op_sel_hi:[1,1,0]
	v_rcp_f32_e32 v71, v67
	v_pk_fma_f32 v[96:97], v[86:87], v[96:97], v[108:109]
	v_pk_fma_f32 v[92:93], v[82:83], v[94:95], 0 op_sel_hi:[1,1,0]
	v_pk_fma_f32 v[106:107], v[86:87], v[94:95], v[106:107]
	s_nop 0
	v_mul_f32_e32 v75, v51, v71
	v_fma_f32 v78, -v67, v75, v51
	v_fma_f32 v70, v78, v71, v75
	v_div_fixup_f32 v51, v70, v67, v51
	v_rcp_f32_e32 v70, v66
	v_pk_fma_f32 v[94:95], v[98:99], v[94:95], v[96:97]
	v_lshlrev_b32_e32 v78, 16, v76
	s_nop 0
	v_mul_f32_e32 v74, v50, v70
	v_fma_f32 v75, -v66, v74, v50
	v_fma_f32 v67, v75, v70, v74
	v_div_fixup_f32 v50, v67, v66, v50
	v_lshlrev_b32_e32 v66, 16, v72
	v_and_b32_e32 v67, 0xffff0000, v72
	v_lshlrev_b32_e32 v70, 16, v68
	v_and_b32_e32 v71, 0xffff0000, v68
	v_pk_fma_f32 v[94:95], v[102:103], v[66:67], v[94:95]
	v_lshlrev_b32_e32 v74, 16, v80
	s_waitcnt vmcnt(0)
	v_pk_fma_f32 v[94:95], v[118:119], v[70:71], v[94:95]
	v_and_b32_e32 v75, 0xffff0000, v80
	v_mul_f32_e32 v56, 0xbfb8aa3b, v94
	v_exp_f32_e32 v96, v56
	v_mul_f32_e32 v56, 0xbfb8aa3b, v95
	v_exp_f32_e32 v97, v56
	v_pk_fma_f32 v[92:93], v[86:87], v[66:67], v[92:93]
	v_pk_mul_f32 v[50:51], v[50:51], s[26:27] op_sel_hi:[1,0]
	v_pk_fma_f32 v[92:93], v[98:99], v[70:71], v[92:93]
	v_pk_add_f32 v[96:97], v[96:97], 1.0 op_sel_hi:[1,0]
	v_pk_fma_f32 v[92:93], v[102:103], v[74:75], v[92:93]
	v_rcp_f32_e32 v60, v97
	v_pk_fma_f32 v[92:93], v[118:119], v[78:79], v[92:93]
	s_nop 0
	v_mul_f32_e32 v68, v95, v60
	v_fma_f32 v72, -v97, v68, v95
	v_fma_f32 v56, v72, v60, v68
	v_div_fixup_f32 v95, v56, v97, v95
	v_rcp_f32_e32 v60, v96
	s_nop 0
	s_nop 0
	v_mul_f32_e32 v68, v94, v60
	v_fma_f32 v72, -v96, v68, v94
	v_fma_f32 v56, v72, v60, v68
	v_div_fixup_f32 v94, v56, v96, v94
	v_pk_mul_f32 v[94:95], v[94:95], s[26:27] op_sel_hi:[1,0]
	s_nop 0
	v_cvt_pk_bf16_f32 v56, v94, v95
	v_pk_fma_f32 v[94:95], v[98:99], v[66:67], v[106:107]
	v_pk_fma_f32 v[66:67], v[82:83], v[66:67], 0 op_sel_hi:[1,1,0]
	v_pk_fma_f32 v[94:95], v[102:103], v[70:71], v[94:95]
	v_pk_fma_f32 v[66:67], v[86:87], v[70:71], v[66:67]
	v_pk_fma_f32 v[94:95], v[118:119], v[74:75], v[94:95]
	v_pk_fma_f32 v[66:67], v[98:99], v[74:75], v[66:67]
	v_mul_f32_e32 v60, 0xbfb8aa3b, v94
	v_exp_f32_e32 v96, v60
	v_mul_f32_e32 v60, 0xbfb8aa3b, v95
	v_exp_f32_e32 v97, v60
	v_pk_fma_f32 v[66:67], v[102:103], v[78:79], v[66:67]
	v_lshlrev_b32_e32 v70, 16, v52
	v_and_b32_e32 v71, 0xffff0000, v52
	v_pk_add_f32 v[96:97], v[96:97], 1.0 op_sel_hi:[1,0]
	v_pk_fma_f32 v[66:67], v[118:119], v[70:71], v[66:67]
	v_rcp_f32_e32 v64, v97
	v_mul_f32_e32 v52, 0xbfb8aa3b, v66
	v_exp_f32_e32 v70, v52
	v_mul_f32_e32 v52, 0xbfb8aa3b, v67
	s_nop 0
	v_mul_f32_e32 v72, v95, v64
	v_fma_f32 v76, -v97, v72, v95
	v_fma_f32 v60, v76, v64, v72
	v_div_fixup_f32 v95, v60, v97, v95
	v_rcp_f32_e32 v64, v96
	v_exp_f32_e32 v71, v52
	v_lshlrev_b32_e32 v86, 16, v57
	v_and_b32_e32 v87, 0xffff0000, v57
	s_nop 0
	v_mul_f32_e32 v72, v94, v64
	v_fma_f32 v76, -v96, v72, v94
	v_fma_f32 v60, v76, v64, v72
	v_div_fixup_f32 v94, v60, v96, v94
	v_pk_mul_f32 v[94:95], v[94:95], s[26:27] op_sel_hi:[1,0]
	v_mul_f32_e32 v64, 0xbfb8aa3b, v92
	v_cvt_pk_bf16_f32 v60, v94, v95
	v_exp_f32_e32 v94, v64
	v_mul_f32_e32 v64, 0xbfb8aa3b, v93
	v_exp_f32_e32 v95, v64
	v_pk_add_f32 v[70:71], v[70:71], 1.0 op_sel_hi:[1,0]
	v_pk_fma_f32 v[86:87], v[84:85], v[86:87], 0 op_sel_hi:[1,1,0]
	v_pk_add_f32 v[94:95], v[94:95], 1.0 op_sel_hi:[1,0]
	v_lshlrev_b32_e32 v78, 16, v65
	v_rcp_f32_e32 v68, v95
	v_and_b32_e32 v79, 0xffff0000, v65
	s_nop 0
	v_mul_f32_e32 v76, v93, v68
	v_fma_f32 v80, -v95, v76, v93
	v_fma_f32 v64, v80, v68, v76
	v_div_fixup_f32 v93, v64, v95, v93
	v_rcp_f32_e32 v68, v94
	s_nop 0
	s_nop 0
	v_mul_f32_e32 v76, v92, v68
	v_fma_f32 v80, -v94, v76, v92
	v_fma_f32 v64, v80, v68, v76
	v_rcp_f32_e32 v68, v71
	v_lshlrev_b32_e32 v80, 16, v61
	v_div_fixup_f32 v92, v64, v94, v92
	v_pk_mul_f32 v[92:93], v[92:93], s[26:27] op_sel_hi:[1,0]
	s_nop 0
	v_mul_f32_e32 v74, v67, v68
	v_fma_f32 v75, -v71, v74, v67
	v_fma_f32 v52, v75, v68, v74
	v_div_fixup_f32 v67, v52, v71, v67
	v_rcp_f32_e32 v68, v70
	v_and_b32_e32 v75, 0xffff0000, v77
	v_cvt_pk_bf16_f32 v64, v92, v93
	s_nop 0
	v_mul_f32_e32 v72, v66, v68
	v_fma_f32 v74, -v70, v72, v66
	v_fma_f32 v52, v74, v68, v72
	v_div_fixup_f32 v66, v52, v70, v66
	v_lshlrev_b32_e32 v70, 16, v73
	v_and_b32_e32 v71, 0xffff0000, v73
	v_lshlrev_b32_e32 v72, 16, v81
	v_and_b32_e32 v73, 0xffff0000, v81
	v_and_b32_e32 v81, 0xffff0000, v61
	v_pk_fma_f32 v[82:83], v[84:85], v[80:81], 0 op_sel_hi:[1,1,0]
	v_pk_fma_f32 v[80:81], v[88:89], v[80:81], v[86:87]
	v_lshlrev_b32_e32 v74, 16, v77
	v_pk_fma_f32 v[76:77], v[84:85], v[78:79], 0 op_sel_hi:[1,1,0]
	v_pk_fma_f32 v[82:83], v[88:89], v[78:79], v[82:83]
	v_pk_fma_f32 v[78:79], v[100:101], v[78:79], v[80:81]
	v_lshlrev_b32_e32 v68, 16, v69
	v_and_b32_e32 v69, 0xffff0000, v69
	v_pk_fma_f32 v[78:79], v[104:105], v[70:71], v[78:79]
	v_pk_fma_f32 v[76:77], v[88:89], v[70:71], v[76:77]
	v_pk_fma_f32 v[78:79], v[120:121], v[68:69], v[78:79]
	v_pk_fma_f32 v[76:77], v[100:101], v[68:69], v[76:77]
	v_mul_f32_e32 v52, 0xbfb8aa3b, v78
	v_exp_f32_e32 v80, v52
	v_mul_f32_e32 v52, 0xbfb8aa3b, v79
	v_exp_f32_e32 v81, v52
	v_pk_fma_f32 v[76:77], v[104:105], v[72:73], v[76:77]
	v_pk_mul_f32 v[66:67], v[66:67], s[26:27] op_sel_hi:[1,0]
	v_pk_fma_f32 v[76:77], v[120:121], v[74:75], v[76:77]
	v_pk_add_f32 v[80:81], v[80:81], 1.0 op_sel_hi:[1,0]
	s_nop 0
	v_rcp_f32_e32 v57, v81
	s_nop 0
	s_nop 0
	v_mul_f32_e32 v65, v79, v57
	v_fma_f32 v86, -v81, v65, v79
	v_fma_f32 v52, v86, v57, v65
	v_div_fixup_f32 v79, v52, v81, v79
	v_rcp_f32_e32 v57, v80
	s_nop 0
	s_nop 0
	v_mul_f32_e32 v65, v78, v57
	v_fma_f32 v81, -v80, v65, v78
	v_fma_f32 v52, v81, v57, v65
	v_div_fixup_f32 v78, v52, v80, v78
	v_pk_mul_f32 v[78:79], v[78:79], s[26:27] op_sel_hi:[1,0]
	s_nop 0
	v_cvt_pk_bf16_f32 v57, v78, v79
	v_pk_fma_f32 v[78:79], v[100:101], v[70:71], v[82:83]
	v_pk_fma_f32 v[70:71], v[84:85], v[70:71], 0 op_sel_hi:[1,1,0]
	v_pk_fma_f32 v[78:79], v[104:105], v[68:69], v[78:79]
	v_pk_fma_f32 v[68:69], v[88:89], v[68:69], v[70:71]
	v_pk_fma_f32 v[78:79], v[120:121], v[72:73], v[78:79]
	v_pk_fma_f32 v[68:69], v[100:101], v[72:73], v[68:69]
	v_mul_f32_e32 v52, 0xbfb8aa3b, v78
	v_exp_f32_e32 v80, v52
	v_mul_f32_e32 v52, 0xbfb8aa3b, v79
	v_exp_f32_e32 v81, v52
	v_pk_fma_f32 v[68:69], v[104:105], v[74:75], v[68:69]
	ds_write_b128 v132, v[54:57] offset:32768
	v_pk_add_f32 v[80:81], v[80:81], 1.0 op_sel_hi:[1,0]
	s_nop 0
	v_rcp_f32_e32 v61, v81
	s_nop 0
	s_nop 0
	v_mul_f32_e32 v82, v79, v61
	v_fma_f32 v83, -v81, v82, v79
	v_fma_f32 v52, v83, v61, v82
	v_div_fixup_f32 v79, v52, v81, v79
	v_rcp_f32_e32 v61, v80
	s_nop 0
	s_nop 0
	v_mul_f32_e32 v81, v78, v61
	v_fma_f32 v82, -v80, v81, v78
	v_fma_f32 v52, v82, v61, v81
	v_div_fixup_f32 v78, v52, v80, v78
	v_pk_mul_f32 v[78:79], v[78:79], s[26:27] op_sel_hi:[1,0]
	v_mul_f32_e32 v52, 0xbfb8aa3b, v76
	v_cvt_pk_bf16_f32 v61, v78, v79
	v_exp_f32_e32 v78, v52
	v_mul_f32_e32 v52, 0xbfb8aa3b, v77
	v_exp_f32_e32 v79, v52
	s_nop 0
	v_pk_add_f32 v[78:79], v[78:79], 1.0 op_sel_hi:[1,0]
	s_nop 0
	v_rcp_f32_e32 v65, v79
	s_nop 0
	s_nop 0
	v_mul_f32_e32 v81, v77, v65
	v_fma_f32 v82, -v79, v81, v77
	v_fma_f32 v52, v82, v65, v81
	v_div_fixup_f32 v77, v52, v79, v77
	v_rcp_f32_e32 v65, v78
	s_nop 0
	s_nop 0
	v_mul_f32_e32 v80, v76, v65
	v_fma_f32 v81, -v78, v80, v76
	v_fma_f32 v52, v81, v65, v80
	v_div_fixup_f32 v76, v52, v78, v76
	v_lshlrev_b32_e32 v52, 16, v53
	v_and_b32_e32 v53, 0xffff0000, v53
	v_pk_fma_f32 v[52:53], v[120:121], v[52:53], v[68:69]
	v_pk_mul_f32 v[76:77], v[76:77], s[26:27] op_sel_hi:[1,0]
	v_mul_f32_e32 v68, 0xbfb8aa3b, v52
	v_mul_f32_e32 v69, 0xbfb8aa3b, v53
	v_exp_f32_e32 v68, v68
	v_exp_f32_e32 v69, v69
	v_cvt_pk_bf16_f32 v65, v76, v77
	v_pk_add_f32 v[68:69], v[68:69], 1.0 op_sel_hi:[1,0]
	s_nop 0
	v_rcp_f32_e32 v71, v69
	s_nop 0
	s_nop 0
	v_mul_f32_e32 v73, v53, v71
	v_fma_f32 v74, -v69, v73, v53
	v_fma_f32 v70, v74, v71, v73
	v_div_fixup_f32 v53, v70, v69, v53
	v_rcp_f32_e32 v70, v68
	s_mov_b64 s[0:1], -1
	s_nop 0
	v_mul_f32_e32 v72, v52, v70
	v_fma_f32 v73, -v68, v72, v52
	v_fma_f32 v69, v73, v70, v72
	v_div_fixup_f32 v52, v69, v68, v52
	v_pk_mul_f32 v[52:53], v[52:53], s[26:27] op_sel_hi:[1,0]
	v_cvt_pk_bf16_f32 v69, v50, v51
	v_lshlrev_b32_e32 v50, 6, v168
	v_cvt_pk_bf16_f32 v71, v52, v53
	v_and_b32_e32 v52, 0xffffc000, v50
	v_and_b32_e32 v50, 48, v176
	v_lshlrev_b32_e32 v51, 3, v170
	v_and_or_b32 v50, v51, 8, v50
	v_lshrrev_b32_e32 v51, 1, v50
	v_lshrrev_b32_e32 v50, 5, v169
	v_or_b32_e32 v51, v51, v50
	v_lshlrev_b32_e32 v53, 9, v51
	v_and_b32_e32 v51, 48, v178
	v_add3_u32 v52, s92, v52, v53
	v_and_b32_e32 v53, 0x100, v134
	v_add3_u32 v52, v52, v51, v53
	s_and_b64 vcc, exec, s[12:13]
	v_cvt_pk_bf16_f32 v68, v90, v91
	v_cvt_pk_bf16_f32 v70, v66, v67
	ds_write_b128 v52, v[34:37]
	ds_write_b128 v133, v[58:61] offset:32768
	ds_write_b128 v52, v[38:41] offset:64
	ds_write_b128 v135, v[62:65] offset:32768
	ds_write_b128 v52, v[42:45] offset:128
	ds_write_b128 v136, v[68:71] offset:32768
	ds_write_b128 v52, v[46:49] offset:192
	s_cbranch_vccz .LBB0_662
	s_cmp_lg_u32 s61, 1
	s_cbranch_scc1 .LBB0_661
	s_ashr_i32 s39, s38, 31
	s_lshl_b64 s[0:1], s[38:39], 9
	s_add_u32 s0, s16, s0
	v_lshlrev_b32_e32 v34, 2, v171
	s_addc_u32 s1, s17, s1
	global_load_dword v35, v34, s[0:1]
	global_load_dword v36, v34, s[0:1] offset:256
	v_add_u32_e32 v34, s94, v34
	s_waitcnt vmcnt(0)
	ds_write2st64_b32 v34, v35, v36 offset0:6 offset1:7
